# v17 + peeled first K-loop trip per GEMM unit (no accumulator clear)
# baseline (speedup 1.0000x reference)
.LBB0_219:
	s_ashr_i32 s63, s62, 31
	s_lshl_b64 s[10:11], s[62:63], 21
	s_add_u32 s10, s56, s10
	s_addc_u32 s11, s57, s11
	s_and_b64 s[24:25], s[92:93], exec
	s_cselect_b32 s30, s11, s91
	s_cselect_b32 s31, s10, s90
	s_ashr_i32 s89, s88, 31
	s_lshl_b64 s[24:25], s[88:89], 21
	s_add_u32 s94, s86, s24
	s_addc_u32 s95, s87, s25
	s_and_b64 s[24:25], s[92:93], exec
	s_cselect_b32 s63, s95, s35
	s_cselect_b32 s81, s94, s34
	s_add_u32 vcc_lo, s90, 0x100080
	s_addc_u32 vcc_hi, s91, 0
	s_add_u32 s82, s34, 0x100
	s_addc_u32 s83, s35, 0
	s_mov_b32 s84, -2
	ds_read_b128 v[152:155], v148
	ds_read_b128 v[156:159], v148 offset:1024
	ds_read_b128 v[160:163], v148 offset:2048
	ds_read_b128 v[164:167], v148 offset:3072
	ds_read_b128 v[168:171], v149
	ds_read_b128 v[176:179], v149 offset:1024
	ds_read_b128 v[180:183], v149 offset:2048
	ds_read_b128 v[184:187], v149 offset:3072
	s_add_u32 s24, vcc_lo, 0xfff00080
	s_addc_u32 s25, vcc_hi, -1
	s_cmp_eq_u32 s84, 60
	s_cselect_b32 s91, s30, s25
	s_cselect_b32 s90, s31, s24
	s_cselect_b32 s35, s63, s83
	s_cselect_b32 s34, s81, s82
	s_mov_b32 m0, s47
	v_lshl_add_u64 v[142:143], vcc, 0, v[138:139]
	ds_read_b128 v[188:191], v150
	ds_read_b128 v[192:195], v150 offset:1024
	ds_read_b128 v[196:199], v150 offset:2048
	ds_read_b128 v[200:203], v150 offset:3072
	ds_read_b128 v[204:207], v150 offset:4096
	ds_read_b128 v[208:211], v150 offset:5120
	ds_read_b128 v[212:215], v150 offset:6144
	ds_read_b128 v[216:219], v150 offset:7168
	global_load_lds_dwordx4 v[142:143], off
	v_lshl_add_u64 v[142:143], vcc, 0, v[140:141]
	s_mov_b32 m0, s50
	s_nop 0
	global_load_lds_dwordx4 v[142:143], off
	s_waitcnt vmcnt(8)
	s_waitcnt lgkmcnt(0)
	s_barrier
	s_setprio 1
	s_waitcnt lgkmcnt(0)
	v_mfma_f32_16x16x32_bf16 v[126:129], v[152:155], v[188:191], 0
	v_mfma_f32_16x16x32_bf16 v[122:125], v[160:163], v[188:191], 0
	v_mfma_f32_16x16x32_bf16 v[114:117], v[152:155], v[196:199], 0
	v_mfma_f32_16x16x32_bf16 v[106:109], v[160:163], v[196:199], 0
	v_mfma_f32_16x16x32_bf16 v[98:101], v[152:155], v[204:207], 0
	v_mfma_f32_16x16x32_bf16 v[90:93], v[160:163], v[204:207], 0
	v_mfma_f32_16x16x32_bf16 v[82:85], v[152:155], v[212:215], 0
	v_mfma_f32_16x16x32_bf16 v[74:77], v[160:163], v[212:215], 0
	v_mfma_f32_16x16x32_bf16 v[126:129], v[156:159], v[192:195], v[126:129]
	v_mfma_f32_16x16x32_bf16 v[122:125], v[164:167], v[192:195], v[122:125]
	v_mfma_f32_16x16x32_bf16 v[114:117], v[156:159], v[200:203], v[114:117]
	v_mfma_f32_16x16x32_bf16 v[106:109], v[164:167], v[200:203], v[106:109]
	v_mfma_f32_16x16x32_bf16 v[98:101], v[156:159], v[208:211], v[98:101]
	v_mfma_f32_16x16x32_bf16 v[90:93], v[164:167], v[208:211], v[90:93]
	v_mfma_f32_16x16x32_bf16 v[82:85], v[156:159], v[216:219], v[82:85]
	v_mfma_f32_16x16x32_bf16 v[74:77], v[164:167], v[216:219], v[74:77]
	s_setprio 0
	s_setprio 1
	v_mfma_f32_16x16x32_bf16 v[118:121], v[168:171], v[188:191], 0
	v_mfma_f32_16x16x32_bf16 v[110:113], v[180:183], v[188:191], 0
	v_mfma_f32_16x16x32_bf16 v[102:105], v[168:171], v[196:199], 0
	v_mfma_f32_16x16x32_bf16 v[94:97], v[180:183], v[196:199], 0
	v_mfma_f32_16x16x32_bf16 v[86:89], v[168:171], v[204:207], 0
	v_mfma_f32_16x16x32_bf16 v[78:81], v[180:183], v[204:207], 0
	v_mfma_f32_16x16x32_bf16 v[70:73], v[168:171], v[212:215], 0
	v_mfma_f32_16x16x32_bf16 v[66:69], v[180:183], v[212:215], 0
	v_mfma_f32_16x16x32_bf16 v[118:121], v[176:179], v[192:195], v[118:121]
	v_mfma_f32_16x16x32_bf16 v[110:113], v[184:187], v[192:195], v[110:113]
	v_mfma_f32_16x16x32_bf16 v[102:105], v[176:179], v[200:203], v[102:105]
	v_mfma_f32_16x16x32_bf16 v[94:97], v[184:187], v[200:203], v[94:97]
	v_mfma_f32_16x16x32_bf16 v[86:89], v[176:179], v[208:211], v[86:89]
	v_mfma_f32_16x16x32_bf16 v[78:81], v[184:187], v[208:211], v[78:81]
	v_mfma_f32_16x16x32_bf16 v[70:73], v[176:179], v[216:219], v[70:73]
	v_mfma_f32_16x16x32_bf16 v[66:69], v[184:187], v[216:219], v[66:69]
	s_setprio 0
	s_barrier
	s_mov_b32 m0, s51
	v_lshl_add_u64 v[142:143], s[34:35], 0, v[132:133]
	s_add_u32 s24, s34, 0x100000
	ds_read_b128 v[188:191], v150 offset:16384
	ds_read_b128 v[192:195], v150 offset:17408
	ds_read_b128 v[196:199], v150 offset:18432
	ds_read_b128 v[200:203], v150 offset:19456
	ds_read_b128 v[204:207], v150 offset:20480
	ds_read_b128 v[208:211], v150 offset:21504
	ds_read_b128 v[212:215], v150 offset:22528
	ds_read_b128 v[216:219], v150 offset:23552
	global_load_lds_dwordx4 v[142:143], off
	v_lshl_add_u64 v[172:173], s[34:35], 0, v[136:137]
	s_mov_b32 m0, s75
	s_addc_u32 s25, s35, 0
	global_load_lds_dwordx4 v[172:173], off
	v_lshl_add_u64 v[220:221], s[24:25], 0, v[132:133]
	s_mov_b32 m0, s78
	v_lshl_add_u64 v[222:223], s[90:91], 0, v[134:135]
	global_load_lds_dwordx4 v[220:221], off
	v_lshl_add_u64 v[220:221], s[24:25], 0, v[136:137]
	s_mov_b32 m0, s79
	s_nop 0
	global_load_lds_dwordx4 v[220:221], off
	v_lshl_add_u64 v[220:221], s[90:91], 0, v[130:131]
	s_mov_b32 m0, s39
	s_nop 0
	global_load_lds_dwordx4 v[220:221], off
	s_mov_b32 m0, s40
	s_nop 0
	global_load_lds_dwordx4 v[222:223], off
	s_waitcnt vmcnt(8)
	s_waitcnt lgkmcnt(0)
	s_barrier
	s_setprio 1
	s_waitcnt lgkmcnt(0)
	v_mfma_f32_16x16x32_bf16 v[62:65], v[152:155], v[188:191], 0
	v_mfma_f32_16x16x32_bf16 v[58:61], v[160:163], v[188:191], 0
	v_mfma_f32_16x16x32_bf16 v[50:53], v[152:155], v[196:199], 0
	v_mfma_f32_16x16x32_bf16 v[42:45], v[160:163], v[196:199], 0
	v_mfma_f32_16x16x32_bf16 v[34:37], v[152:155], v[204:207], 0
	v_mfma_f32_16x16x32_bf16 v[26:29], v[160:163], v[204:207], 0
	v_mfma_f32_16x16x32_bf16 v[18:21], v[152:155], v[212:215], 0
	v_mfma_f32_16x16x32_bf16 v[10:13], v[160:163], v[212:215], 0
	v_mfma_f32_16x16x32_bf16 v[62:65], v[156:159], v[192:195], v[62:65]
	v_mfma_f32_16x16x32_bf16 v[58:61], v[164:167], v[192:195], v[58:61]
	v_mfma_f32_16x16x32_bf16 v[50:53], v[156:159], v[200:203], v[50:53]
	v_mfma_f32_16x16x32_bf16 v[42:45], v[164:167], v[200:203], v[42:45]
	v_mfma_f32_16x16x32_bf16 v[34:37], v[156:159], v[208:211], v[34:37]
	v_mfma_f32_16x16x32_bf16 v[26:29], v[164:167], v[208:211], v[26:29]
	v_mfma_f32_16x16x32_bf16 v[18:21], v[156:159], v[216:219], v[18:21]
	v_mfma_f32_16x16x32_bf16 v[10:13], v[164:167], v[216:219], v[10:13]
	s_setprio 0
	s_setprio 1
	v_mfma_f32_16x16x32_bf16 v[54:57], v[168:171], v[188:191], 0
	v_mfma_f32_16x16x32_bf16 v[46:49], v[180:183], v[188:191], 0
	v_mfma_f32_16x16x32_bf16 v[38:41], v[168:171], v[196:199], 0
	v_mfma_f32_16x16x32_bf16 v[30:33], v[180:183], v[196:199], 0
	v_mfma_f32_16x16x32_bf16 v[22:25], v[168:171], v[204:207], 0
	v_mfma_f32_16x16x32_bf16 v[14:17], v[180:183], v[204:207], 0
	v_mfma_f32_16x16x32_bf16 v[6:9], v[168:171], v[212:215], 0
	v_mfma_f32_16x16x32_bf16 v[2:5], v[180:183], v[212:215], 0
	v_mfma_f32_16x16x32_bf16 v[54:57], v[176:179], v[192:195], v[54:57]
	v_mfma_f32_16x16x32_bf16 v[46:49], v[184:187], v[192:195], v[46:49]
	v_mfma_f32_16x16x32_bf16 v[38:41], v[176:179], v[200:203], v[38:41]
	v_mfma_f32_16x16x32_bf16 v[30:33], v[184:187], v[200:203], v[30:33]
	v_mfma_f32_16x16x32_bf16 v[22:25], v[176:179], v[208:211], v[22:25]
	v_mfma_f32_16x16x32_bf16 v[14:17], v[184:187], v[208:211], v[14:17]
	v_mfma_f32_16x16x32_bf16 v[6:9], v[176:179], v[216:219], v[6:9]
	v_mfma_f32_16x16x32_bf16 v[2:5], v[184:187], v[216:219], v[2:5]
	s_setprio 0
	s_barrier
	s_add_i32 s85, 0, 0x1c000
	v_add_u32_e32 v175, s85, v146
	ds_read_b128 v[152:155], v151
	ds_read_b128 v[156:159], v151 offset:1024
	ds_read_b128 v[160:163], v151 offset:2048
	ds_read_b128 v[164:167], v151 offset:3072
	ds_read_b128 v[168:171], v175
	ds_read_b128 v[176:179], v175 offset:1024
	ds_read_b128 v[180:183], v175 offset:2048
	ds_read_b128 v[184:187], v175 offset:3072
	s_add_u32 s24, s90, 0x100000
	s_addc_u32 s25, s91, 0
	s_mov_b32 m0, s41
	v_lshl_add_u64 v[224:225], s[24:25], 0, v[130:131]
	ds_read_b128 v[188:191], v150 offset:32768
	ds_read_b128 v[192:195], v150 offset:33792
	ds_read_b128 v[196:199], v150 offset:34816
	ds_read_b128 v[200:203], v150 offset:35840
	ds_read_b128 v[204:207], v150 offset:36864
	ds_read_b128 v[208:211], v150 offset:37888
	ds_read_b128 v[212:215], v150 offset:38912
	ds_read_b128 v[216:219], v150 offset:39936
	global_load_lds_dwordx4 v[224:225], off
	v_lshl_add_u64 v[224:225], s[24:25], 0, v[134:135]
	s_mov_b32 m0, s42
	s_nop 0
	global_load_lds_dwordx4 v[224:225], off
	s_waitcnt vmcnt(8)
	s_waitcnt lgkmcnt(0)
	s_barrier
	s_setprio 1
	s_waitcnt lgkmcnt(0)
	v_mfma_f32_16x16x32_bf16 v[126:129], v[152:155], v[188:191], v[126:129]
	v_mfma_f32_16x16x32_bf16 v[122:125], v[160:163], v[188:191], v[122:125]
	v_mfma_f32_16x16x32_bf16 v[114:117], v[152:155], v[196:199], v[114:117]
	v_mfma_f32_16x16x32_bf16 v[106:109], v[160:163], v[196:199], v[106:109]
	v_mfma_f32_16x16x32_bf16 v[98:101], v[152:155], v[204:207], v[98:101]
	v_mfma_f32_16x16x32_bf16 v[90:93], v[160:163], v[204:207], v[90:93]
	v_mfma_f32_16x16x32_bf16 v[82:85], v[152:155], v[212:215], v[82:85]
	v_mfma_f32_16x16x32_bf16 v[74:77], v[160:163], v[212:215], v[74:77]
	v_mfma_f32_16x16x32_bf16 v[126:129], v[156:159], v[192:195], v[126:129]
	v_mfma_f32_16x16x32_bf16 v[122:125], v[164:167], v[192:195], v[122:125]
	v_mfma_f32_16x16x32_bf16 v[114:117], v[156:159], v[200:203], v[114:117]
	v_mfma_f32_16x16x32_bf16 v[106:109], v[164:167], v[200:203], v[106:109]
	v_mfma_f32_16x16x32_bf16 v[98:101], v[156:159], v[208:211], v[98:101]
	v_mfma_f32_16x16x32_bf16 v[90:93], v[164:167], v[208:211], v[90:93]
	v_mfma_f32_16x16x32_bf16 v[82:85], v[156:159], v[216:219], v[82:85]
	v_mfma_f32_16x16x32_bf16 v[74:77], v[164:167], v[216:219], v[74:77]
	s_setprio 0
	s_setprio 1
	v_mfma_f32_16x16x32_bf16 v[118:121], v[168:171], v[188:191], v[118:121]
	v_mfma_f32_16x16x32_bf16 v[110:113], v[180:183], v[188:191], v[110:113]
	v_mfma_f32_16x16x32_bf16 v[102:105], v[168:171], v[196:199], v[102:105]
	v_mfma_f32_16x16x32_bf16 v[94:97], v[180:183], v[196:199], v[94:97]
	v_mfma_f32_16x16x32_bf16 v[86:89], v[168:171], v[204:207], v[86:89]
	v_mfma_f32_16x16x32_bf16 v[78:81], v[180:183], v[204:207], v[78:81]
	v_mfma_f32_16x16x32_bf16 v[70:73], v[168:171], v[212:215], v[70:73]
	v_mfma_f32_16x16x32_bf16 v[66:69], v[180:183], v[212:215], v[66:69]
	v_mfma_f32_16x16x32_bf16 v[118:121], v[176:179], v[192:195], v[118:121]
	v_mfma_f32_16x16x32_bf16 v[110:113], v[184:187], v[192:195], v[110:113]
	v_mfma_f32_16x16x32_bf16 v[102:105], v[176:179], v[200:203], v[102:105]
	v_mfma_f32_16x16x32_bf16 v[94:97], v[184:187], v[200:203], v[94:97]
	v_mfma_f32_16x16x32_bf16 v[86:89], v[176:179], v[208:211], v[86:89]
	v_mfma_f32_16x16x32_bf16 v[78:81], v[184:187], v[208:211], v[78:81]
	v_mfma_f32_16x16x32_bf16 v[70:73], v[176:179], v[216:219], v[70:73]
	v_mfma_f32_16x16x32_bf16 v[66:69], v[184:187], v[216:219], v[66:69]
	s_setprio 0
	s_barrier
	s_add_i32 s24, s80, s37
	v_lshl_add_u64 v[142:143], v[142:143], 0, s[8:9]
	s_mov_b32 m0, s24
	ds_read_b128 v[188:191], v150 offset:49152
	ds_read_b128 v[192:195], v150 offset:50176
	ds_read_b128 v[196:199], v150 offset:51200
	ds_read_b128 v[200:203], v150 offset:52224
	ds_read_b128 v[204:207], v150 offset:53248
	ds_read_b128 v[208:211], v150 offset:54272
	ds_read_b128 v[212:215], v150 offset:55296
	ds_read_b128 v[216:219], v150 offset:56320
	global_load_lds_dwordx4 v[142:143], off
	s_add_i32 m0, s24, 0x2000
	s_add_u32 s24, s34, 0x100080
	v_lshl_add_u64 v[142:143], v[172:173], 0, s[8:9]
	s_addc_u32 s25, s35, 0
	s_add_i32 s34, s85, s37
	global_load_lds_dwordx4 v[142:143], off
	v_lshl_add_u64 v[142:143], s[24:25], 0, v[132:133]
	s_mov_b32 m0, s34
	s_nop 0
	global_load_lds_dwordx4 v[142:143], off
	v_lshl_add_u64 v[142:143], s[24:25], 0, v[136:137]
	s_add_i32 m0, s34, 0x2000
	s_nop 0
	global_load_lds_dwordx4 v[142:143], off
	v_lshl_add_u64 v[142:143], v[220:221], 0, s[8:9]
	s_mov_b32 m0, s43
	s_nop 0
	global_load_lds_dwordx4 v[142:143], off
	v_lshl_add_u64 v[142:143], v[222:223], 0, s[8:9]
	s_mov_b32 m0, s44
	s_nop 0
	global_load_lds_dwordx4 v[142:143], off
	s_waitcnt vmcnt(8)
	s_waitcnt lgkmcnt(0)
	s_barrier
	s_setprio 1
	s_waitcnt lgkmcnt(0)
	v_mfma_f32_16x16x32_bf16 v[62:65], v[152:155], v[188:191], v[62:65]
	v_mfma_f32_16x16x32_bf16 v[58:61], v[160:163], v[188:191], v[58:61]
	v_mfma_f32_16x16x32_bf16 v[50:53], v[152:155], v[196:199], v[50:53]
	v_mfma_f32_16x16x32_bf16 v[42:45], v[160:163], v[196:199], v[42:45]
	v_mfma_f32_16x16x32_bf16 v[34:37], v[152:155], v[204:207], v[34:37]
	v_mfma_f32_16x16x32_bf16 v[26:29], v[160:163], v[204:207], v[26:29]
	v_mfma_f32_16x16x32_bf16 v[18:21], v[152:155], v[212:215], v[18:21]
	v_mfma_f32_16x16x32_bf16 v[10:13], v[160:163], v[212:215], v[10:13]
	v_mfma_f32_16x16x32_bf16 v[62:65], v[156:159], v[192:195], v[62:65]
	v_mfma_f32_16x16x32_bf16 v[58:61], v[164:167], v[192:195], v[58:61]
	v_mfma_f32_16x16x32_bf16 v[50:53], v[156:159], v[200:203], v[50:53]
	v_mfma_f32_16x16x32_bf16 v[42:45], v[164:167], v[200:203], v[42:45]
	v_mfma_f32_16x16x32_bf16 v[34:37], v[156:159], v[208:211], v[34:37]
	v_mfma_f32_16x16x32_bf16 v[26:29], v[164:167], v[208:211], v[26:29]
	v_mfma_f32_16x16x32_bf16 v[18:21], v[156:159], v[216:219], v[18:21]
	v_mfma_f32_16x16x32_bf16 v[10:13], v[164:167], v[216:219], v[10:13]
	s_setprio 0
	s_setprio 1
	v_mfma_f32_16x16x32_bf16 v[54:57], v[168:171], v[188:191], v[54:57]
	v_mfma_f32_16x16x32_bf16 v[46:49], v[180:183], v[188:191], v[46:49]
	v_mfma_f32_16x16x32_bf16 v[38:41], v[168:171], v[196:199], v[38:41]
	v_mfma_f32_16x16x32_bf16 v[30:33], v[180:183], v[196:199], v[30:33]
	v_mfma_f32_16x16x32_bf16 v[22:25], v[168:171], v[204:207], v[22:25]
	v_mfma_f32_16x16x32_bf16 v[14:17], v[180:183], v[204:207], v[14:17]
	v_mfma_f32_16x16x32_bf16 v[6:9], v[168:171], v[212:215], v[6:9]
	v_mfma_f32_16x16x32_bf16 v[2:5], v[180:183], v[212:215], v[2:5]
	v_mfma_f32_16x16x32_bf16 v[54:57], v[176:179], v[192:195], v[54:57]
	v_mfma_f32_16x16x32_bf16 v[46:49], v[184:187], v[192:195], v[46:49]
	v_mfma_f32_16x16x32_bf16 v[38:41], v[176:179], v[200:203], v[38:41]
	v_mfma_f32_16x16x32_bf16 v[30:33], v[184:187], v[200:203], v[30:33]
	v_mfma_f32_16x16x32_bf16 v[22:25], v[176:179], v[208:211], v[22:25]
	v_mfma_f32_16x16x32_bf16 v[14:17], v[184:187], v[208:211], v[14:17]
	v_mfma_f32_16x16x32_bf16 v[6:9], v[176:179], v[216:219], v[6:9]
	v_mfma_f32_16x16x32_bf16 v[2:5], v[184:187], v[216:219], v[2:5]
	s_setprio 0
	s_barrier
	s_add_i32 s84, s84, 2
	s_add_u32 vcc_lo, vcc_lo, 0x100
	s_addc_u32 vcc_hi, vcc_hi, 0
	s_add_u32 s82, s82, 0x100
	s_addc_u32 s83, s83, 0
	s_cmp_gt_u32 s84, 61
	s_cbranch_scc1 .Lpeel_exit_0

.Lpeel_exit_0:
	s_and_b64 vcc, exec, s[60:61]
	s_cbranch_vccz .LBB0_223
	s_barrier

.LBB0_562:
	s_ashr_i32 s61, s60, 31
	s_lshl_b64 s[24:25], s[60:61], 20
	s_add_u32 s62, s42, s24
	s_addc_u32 s63, s43, s25
	s_and_b64 s[24:25], s[4:5], exec
	s_cselect_b32 s30, s63, s11
	s_cselect_b32 s31, s62, s10
	s_ashr_i32 s47, s46, 31
	s_lshl_b64 s[24:25], s[46:47], 20
	s_add_u32 s78, s58, s24
	s_addc_u32 s79, s59, s25
	s_and_b64 s[24:25], s[4:5], exec
	s_cselect_b32 s47, s79, s35
	s_cselect_b32 s61, s78, s34
	s_add_u32 s82, s10, 0x80080
	s_addc_u32 s83, s11, 0
	s_add_u32 s91, s34, 0x100
	s_addc_u32 s92, s35, 0
	s_mov_b32 s93, -2
	s_waitcnt vmcnt(0)
	ds_read_b128 v[130:133], v187
	ds_read_b128 v[134:137], v187 offset:1024
	ds_read_b128 v[138:141], v187 offset:2048
	ds_read_b128 v[142:145], v187 offset:3072
	ds_read_b128 v[146:149], v188
	ds_read_b128 v[158:161], v188 offset:1024
	ds_read_b128 v[162:165], v188 offset:2048
	ds_read_b128 v[190:193], v188 offset:3072
	s_add_u32 s10, s82, 0xfff80080
	s_addc_u32 s11, s83, -1
	s_cmp_eq_u32 s93, 28
	s_cselect_b32 s35, s30, s11
	s_cselect_b32 s34, s31, s10
	s_cselect_b32 s11, s47, s92
	s_cselect_b32 s10, s61, s91
	v_lshl_add_u64 v[166:167], s[82:83], 0, v[150:151]
	s_add_i32 m0, s45, 0xc000
	ds_read_b128 v[194:197], v189
	ds_read_b128 v[198:201], v189 offset:1024
	ds_read_b128 v[202:205], v189 offset:2048
	ds_read_b128 v[206:209], v189 offset:3072
	ds_read_b128 v[210:213], v189 offset:4096
	ds_read_b128 v[214:217], v189 offset:5120
	ds_read_b128 v[218:221], v189 offset:6144
	ds_read_b128 v[222:225], v189 offset:7168
	global_load_lds_dwordx4 v[166:167], off
	v_lshl_add_u64 v[166:167], s[82:83], 0, v[152:153]
	s_add_i32 m0, s45, 0xe000
	s_nop 0
	global_load_lds_dwordx4 v[166:167], off
	s_waitcnt vmcnt(8)
	s_waitcnt lgkmcnt(0)
	s_barrier
	s_setprio 1
	s_waitcnt lgkmcnt(0)
	v_mfma_f32_16x16x32_bf16 v[126:129], v[130:133], v[194:197], 0
	v_mfma_f32_16x16x32_bf16 v[122:125], v[138:141], v[194:197], 0
	v_mfma_f32_16x16x32_bf16 v[110:113], v[130:133], v[202:205], 0
	v_mfma_f32_16x16x32_bf16 v[106:109], v[138:141], v[202:205], 0
	v_mfma_f32_16x16x32_bf16 v[94:97], v[130:133], v[210:213], 0
	v_mfma_f32_16x16x32_bf16 v[90:93], v[138:141], v[210:213], 0
	v_mfma_f32_16x16x32_bf16 v[78:81], v[130:133], v[218:221], 0
	v_mfma_f32_16x16x32_bf16 v[74:77], v[138:141], v[218:221], 0
	v_mfma_f32_16x16x32_bf16 v[126:129], v[134:137], v[198:201], v[126:129]
	v_mfma_f32_16x16x32_bf16 v[122:125], v[142:145], v[198:201], v[122:125]
	v_mfma_f32_16x16x32_bf16 v[110:113], v[134:137], v[206:209], v[110:113]
	v_mfma_f32_16x16x32_bf16 v[106:109], v[142:145], v[206:209], v[106:109]
	v_mfma_f32_16x16x32_bf16 v[94:97], v[134:137], v[214:217], v[94:97]
	v_mfma_f32_16x16x32_bf16 v[90:93], v[142:145], v[214:217], v[90:93]
	v_mfma_f32_16x16x32_bf16 v[78:81], v[134:137], v[222:225], v[78:81]
	v_mfma_f32_16x16x32_bf16 v[74:77], v[142:145], v[222:225], v[74:77]
	s_setprio 0
	s_setprio 1
	v_mfma_f32_16x16x32_bf16 v[118:121], v[146:149], v[194:197], 0
	v_mfma_f32_16x16x32_bf16 v[114:117], v[162:165], v[194:197], 0
	v_mfma_f32_16x16x32_bf16 v[102:105], v[146:149], v[202:205], 0
	v_mfma_f32_16x16x32_bf16 v[98:101], v[162:165], v[202:205], 0
	v_mfma_f32_16x16x32_bf16 v[86:89], v[146:149], v[210:213], 0
	v_mfma_f32_16x16x32_bf16 v[82:85], v[162:165], v[210:213], 0
	v_mfma_f32_16x16x32_bf16 v[70:73], v[146:149], v[218:221], 0
	v_mfma_f32_16x16x32_bf16 v[66:69], v[162:165], v[218:221], 0
	v_mfma_f32_16x16x32_bf16 v[118:121], v[158:161], v[198:201], v[118:121]
	v_mfma_f32_16x16x32_bf16 v[114:117], v[190:193], v[198:201], v[114:117]
	v_mfma_f32_16x16x32_bf16 v[102:105], v[158:161], v[206:209], v[102:105]
	v_mfma_f32_16x16x32_bf16 v[98:101], v[190:193], v[206:209], v[98:101]
	v_mfma_f32_16x16x32_bf16 v[86:89], v[158:161], v[214:217], v[86:89]
	v_mfma_f32_16x16x32_bf16 v[82:85], v[190:193], v[214:217], v[82:85]
	v_mfma_f32_16x16x32_bf16 v[70:73], v[158:161], v[222:225], v[70:73]
	v_mfma_f32_16x16x32_bf16 v[66:69], v[190:193], v[222:225], v[66:69]
	s_setprio 0
	s_barrier
	s_add_i32 s24, s87, s3
	v_lshl_add_u64 v[166:167], s[10:11], 0, v[178:179]
	s_mov_b32 m0, s24
	ds_read_b128 v[194:197], v189 offset:16384
	ds_read_b128 v[198:201], v189 offset:17408
	ds_read_b128 v[202:205], v189 offset:18432
	ds_read_b128 v[206:209], v189 offset:19456
	ds_read_b128 v[210:213], v189 offset:20480
	ds_read_b128 v[214:217], v189 offset:21504
	ds_read_b128 v[218:221], v189 offset:22528
	ds_read_b128 v[222:225], v189 offset:23552
	global_load_lds_dwordx4 v[166:167], off
	s_add_i32 m0, s24, 0x2000
	s_add_u32 s24, s10, 0x80000
	v_lshl_add_u64 v[226:227], s[10:11], 0, v[182:183]
	s_addc_u32 s25, s11, 0
	s_add_i32 s94, s88, s3
	global_load_lds_dwordx4 v[226:227], off
	v_lshl_add_u64 v[228:229], s[24:25], 0, v[178:179]
	s_mov_b32 m0, s94
	v_lshl_add_u64 v[230:231], s[34:35], 0, v[180:181]
	global_load_lds_dwordx4 v[228:229], off
	v_lshl_add_u64 v[228:229], s[24:25], 0, v[182:183]
	s_add_i32 m0, s94, 0x2000
	s_nop 0
	global_load_lds_dwordx4 v[228:229], off
	v_lshl_add_u64 v[228:229], s[34:35], 0, v[176:177]
	s_mov_b32 m0, s45
	s_nop 0
	global_load_lds_dwordx4 v[228:229], off
	s_mov_b32 m0, s50
	s_nop 0
	global_load_lds_dwordx4 v[230:231], off
	s_waitcnt vmcnt(8)
	s_waitcnt lgkmcnt(0)
	s_barrier
	s_setprio 1
	s_waitcnt lgkmcnt(0)
	v_mfma_f32_16x16x32_bf16 v[62:65], v[130:133], v[194:197], 0
	v_mfma_f32_16x16x32_bf16 v[58:61], v[138:141], v[194:197], 0
	v_mfma_f32_16x16x32_bf16 v[46:49], v[130:133], v[202:205], 0
	v_mfma_f32_16x16x32_bf16 v[42:45], v[138:141], v[202:205], 0
	v_mfma_f32_16x16x32_bf16 v[30:33], v[130:133], v[210:213], 0
	v_mfma_f32_16x16x32_bf16 v[26:29], v[138:141], v[210:213], 0
	v_mfma_f32_16x16x32_bf16 v[14:17], v[130:133], v[218:221], 0
	v_mfma_f32_16x16x32_bf16 v[10:13], v[138:141], v[218:221], 0
	v_mfma_f32_16x16x32_bf16 v[62:65], v[134:137], v[198:201], v[62:65]
	v_mfma_f32_16x16x32_bf16 v[58:61], v[142:145], v[198:201], v[58:61]
	v_mfma_f32_16x16x32_bf16 v[46:49], v[134:137], v[206:209], v[46:49]
	v_mfma_f32_16x16x32_bf16 v[42:45], v[142:145], v[206:209], v[42:45]
	v_mfma_f32_16x16x32_bf16 v[30:33], v[134:137], v[214:217], v[30:33]
	v_mfma_f32_16x16x32_bf16 v[26:29], v[142:145], v[214:217], v[26:29]
	v_mfma_f32_16x16x32_bf16 v[14:17], v[134:137], v[222:225], v[14:17]
	v_mfma_f32_16x16x32_bf16 v[10:13], v[142:145], v[222:225], v[10:13]
	s_setprio 0
	s_setprio 1
	v_mfma_f32_16x16x32_bf16 v[54:57], v[146:149], v[194:197], 0
	v_mfma_f32_16x16x32_bf16 v[50:53], v[162:165], v[194:197], 0
	v_mfma_f32_16x16x32_bf16 v[38:41], v[146:149], v[202:205], 0
	v_mfma_f32_16x16x32_bf16 v[34:37], v[162:165], v[202:205], 0
	v_mfma_f32_16x16x32_bf16 v[22:25], v[146:149], v[210:213], 0
	v_mfma_f32_16x16x32_bf16 v[18:21], v[162:165], v[210:213], 0
	v_mfma_f32_16x16x32_bf16 v[6:9], v[146:149], v[218:221], 0
	v_mfma_f32_16x16x32_bf16 v[2:5], v[162:165], v[218:221], 0
	v_mfma_f32_16x16x32_bf16 v[54:57], v[158:161], v[198:201], v[54:57]
	v_mfma_f32_16x16x32_bf16 v[50:53], v[190:193], v[198:201], v[50:53]
	v_mfma_f32_16x16x32_bf16 v[38:41], v[158:161], v[206:209], v[38:41]
	v_mfma_f32_16x16x32_bf16 v[34:37], v[190:193], v[206:209], v[34:37]
	v_mfma_f32_16x16x32_bf16 v[22:25], v[158:161], v[214:217], v[22:25]
	v_mfma_f32_16x16x32_bf16 v[18:21], v[190:193], v[214:217], v[18:21]
	v_mfma_f32_16x16x32_bf16 v[6:9], v[158:161], v[222:225], v[6:9]
	v_mfma_f32_16x16x32_bf16 v[2:5], v[190:193], v[222:225], v[2:5]
	s_setprio 0
	s_barrier
	s_add_i32 s94, 0, 0x18000
	s_add_i32 s95, 0, 0x1c000
	v_add_u32_e32 v142, s94, v185
	v_add_u32_e32 v190, s95, v185
	ds_read_b128 v[130:133], v142
	ds_read_b128 v[134:137], v142 offset:1024
	ds_read_b128 v[138:141], v142 offset:2048
	ds_read_b128 v[142:145], v142 offset:3072
	ds_read_b128 v[146:149], v190
	ds_read_b128 v[158:161], v190 offset:1024
	ds_read_b128 v[162:165], v190 offset:2048
	ds_read_b128 v[190:193], v190 offset:3072
	s_add_u32 s24, s34, 0x80000
	s_addc_u32 s25, s35, 0
	s_mov_b32 m0, s51
	v_lshl_add_u64 v[232:233], s[24:25], 0, v[176:177]
	ds_read_b128 v[194:197], v189 offset:32768
	ds_read_b128 v[198:201], v189 offset:33792
	ds_read_b128 v[202:205], v189 offset:34816
	ds_read_b128 v[206:209], v189 offset:35840
	ds_read_b128 v[210:213], v189 offset:36864
	ds_read_b128 v[214:217], v189 offset:37888
	ds_read_b128 v[218:221], v189 offset:38912
	ds_read_b128 v[222:225], v189 offset:39936
	global_load_lds_dwordx4 v[232:233], off
	v_lshl_add_u64 v[232:233], s[24:25], 0, v[180:181]
	s_mov_b32 m0, s75
	s_nop 0
	global_load_lds_dwordx4 v[232:233], off
	s_waitcnt vmcnt(8)
	s_waitcnt lgkmcnt(0)
	s_barrier
	s_setprio 1
	s_waitcnt lgkmcnt(0)
	v_mfma_f32_16x16x32_bf16 v[126:129], v[130:133], v[194:197], v[126:129]
	v_mfma_f32_16x16x32_bf16 v[122:125], v[138:141], v[194:197], v[122:125]
	v_mfma_f32_16x16x32_bf16 v[110:113], v[130:133], v[202:205], v[110:113]
	v_mfma_f32_16x16x32_bf16 v[106:109], v[138:141], v[202:205], v[106:109]
	v_mfma_f32_16x16x32_bf16 v[94:97], v[130:133], v[210:213], v[94:97]
	v_mfma_f32_16x16x32_bf16 v[90:93], v[138:141], v[210:213], v[90:93]
	v_mfma_f32_16x16x32_bf16 v[78:81], v[130:133], v[218:221], v[78:81]
	v_mfma_f32_16x16x32_bf16 v[74:77], v[138:141], v[218:221], v[74:77]
	v_mfma_f32_16x16x32_bf16 v[126:129], v[134:137], v[198:201], v[126:129]
	v_mfma_f32_16x16x32_bf16 v[122:125], v[142:145], v[198:201], v[122:125]
	v_mfma_f32_16x16x32_bf16 v[110:113], v[134:137], v[206:209], v[110:113]
	v_mfma_f32_16x16x32_bf16 v[106:109], v[142:145], v[206:209], v[106:109]
	v_mfma_f32_16x16x32_bf16 v[94:97], v[134:137], v[214:217], v[94:97]
	v_mfma_f32_16x16x32_bf16 v[90:93], v[142:145], v[214:217], v[90:93]
	v_mfma_f32_16x16x32_bf16 v[78:81], v[134:137], v[222:225], v[78:81]
	v_mfma_f32_16x16x32_bf16 v[74:77], v[142:145], v[222:225], v[74:77]
	s_setprio 0
	s_setprio 1
	v_mfma_f32_16x16x32_bf16 v[118:121], v[146:149], v[194:197], v[118:121]
	v_mfma_f32_16x16x32_bf16 v[114:117], v[162:165], v[194:197], v[114:117]
	v_mfma_f32_16x16x32_bf16 v[102:105], v[146:149], v[202:205], v[102:105]
	v_mfma_f32_16x16x32_bf16 v[98:101], v[162:165], v[202:205], v[98:101]
	v_mfma_f32_16x16x32_bf16 v[86:89], v[146:149], v[210:213], v[86:89]
	v_mfma_f32_16x16x32_bf16 v[82:85], v[162:165], v[210:213], v[82:85]
	v_mfma_f32_16x16x32_bf16 v[70:73], v[146:149], v[218:221], v[70:73]
	v_mfma_f32_16x16x32_bf16 v[66:69], v[162:165], v[218:221], v[66:69]
	v_mfma_f32_16x16x32_bf16 v[118:121], v[158:161], v[198:201], v[118:121]
	v_mfma_f32_16x16x32_bf16 v[114:117], v[190:193], v[198:201], v[114:117]
	v_mfma_f32_16x16x32_bf16 v[102:105], v[158:161], v[206:209], v[102:105]
	v_mfma_f32_16x16x32_bf16 v[98:101], v[190:193], v[206:209], v[98:101]
	v_mfma_f32_16x16x32_bf16 v[86:89], v[158:161], v[214:217], v[86:89]
	v_mfma_f32_16x16x32_bf16 v[82:85], v[190:193], v[214:217], v[82:85]
	v_mfma_f32_16x16x32_bf16 v[70:73], v[158:161], v[222:225], v[70:73]
	v_mfma_f32_16x16x32_bf16 v[66:69], v[190:193], v[222:225], v[66:69]
	s_setprio 0
	s_barrier
	s_add_i32 s24, s94, s3
	v_lshl_add_u64 v[166:167], v[166:167], 0, s[38:39]
	s_mov_b32 m0, s24
	ds_read_b128 v[194:197], v189 offset:49152
	ds_read_b128 v[198:201], v189 offset:50176
	ds_read_b128 v[202:205], v189 offset:51200
	ds_read_b128 v[206:209], v189 offset:52224
	ds_read_b128 v[210:213], v189 offset:53248
	ds_read_b128 v[214:217], v189 offset:54272
	ds_read_b128 v[218:221], v189 offset:55296
	ds_read_b128 v[222:225], v189 offset:56320
	global_load_lds_dwordx4 v[166:167], off
	s_add_i32 m0, s24, 0x2000
	s_add_u32 s10, s10, 0x80080
	v_lshl_add_u64 v[166:167], v[226:227], 0, s[38:39]
	s_addc_u32 s11, s11, 0
	s_add_i32 s24, s95, s3
	global_load_lds_dwordx4 v[166:167], off
	v_lshl_add_u64 v[166:167], s[10:11], 0, v[178:179]
	s_mov_b32 m0, s24
	s_nop 0
	global_load_lds_dwordx4 v[166:167], off
	v_lshl_add_u64 v[166:167], s[10:11], 0, v[182:183]
	s_add_i32 m0, s24, 0x2000
	s_nop 0
	global_load_lds_dwordx4 v[166:167], off
	v_lshl_add_u64 v[166:167], v[228:229], 0, s[38:39]
	s_mov_b32 m0, s84
	s_nop 0
	global_load_lds_dwordx4 v[166:167], off
	v_lshl_add_u64 v[166:167], v[230:231], 0, s[38:39]
	s_mov_b32 m0, s85
	s_nop 0
	global_load_lds_dwordx4 v[166:167], off
	s_waitcnt vmcnt(8)
	s_waitcnt lgkmcnt(0)
	s_barrier
	s_setprio 1
	s_waitcnt lgkmcnt(0)
	v_mfma_f32_16x16x32_bf16 v[62:65], v[130:133], v[194:197], v[62:65]
	v_mfma_f32_16x16x32_bf16 v[58:61], v[138:141], v[194:197], v[58:61]
	v_mfma_f32_16x16x32_bf16 v[46:49], v[130:133], v[202:205], v[46:49]
	v_mfma_f32_16x16x32_bf16 v[42:45], v[138:141], v[202:205], v[42:45]
	v_mfma_f32_16x16x32_bf16 v[30:33], v[130:133], v[210:213], v[30:33]
	v_mfma_f32_16x16x32_bf16 v[26:29], v[138:141], v[210:213], v[26:29]
	v_mfma_f32_16x16x32_bf16 v[14:17], v[130:133], v[218:221], v[14:17]
	v_mfma_f32_16x16x32_bf16 v[10:13], v[138:141], v[218:221], v[10:13]
	v_mfma_f32_16x16x32_bf16 v[62:65], v[134:137], v[198:201], v[62:65]
	v_mfma_f32_16x16x32_bf16 v[58:61], v[142:145], v[198:201], v[58:61]
	v_mfma_f32_16x16x32_bf16 v[46:49], v[134:137], v[206:209], v[46:49]
	v_mfma_f32_16x16x32_bf16 v[42:45], v[142:145], v[206:209], v[42:45]
	v_mfma_f32_16x16x32_bf16 v[30:33], v[134:137], v[214:217], v[30:33]
	v_mfma_f32_16x16x32_bf16 v[26:29], v[142:145], v[214:217], v[26:29]
	v_mfma_f32_16x16x32_bf16 v[14:17], v[134:137], v[222:225], v[14:17]
	v_mfma_f32_16x16x32_bf16 v[10:13], v[142:145], v[222:225], v[10:13]
	s_setprio 0
	s_setprio 1
	v_mfma_f32_16x16x32_bf16 v[54:57], v[146:149], v[194:197], v[54:57]
	v_mfma_f32_16x16x32_bf16 v[50:53], v[162:165], v[194:197], v[50:53]
	v_mfma_f32_16x16x32_bf16 v[38:41], v[146:149], v[202:205], v[38:41]
	v_mfma_f32_16x16x32_bf16 v[34:37], v[162:165], v[202:205], v[34:37]
	v_mfma_f32_16x16x32_bf16 v[22:25], v[146:149], v[210:213], v[22:25]
	v_mfma_f32_16x16x32_bf16 v[18:21], v[162:165], v[210:213], v[18:21]
	v_mfma_f32_16x16x32_bf16 v[6:9], v[146:149], v[218:221], v[6:9]
	v_mfma_f32_16x16x32_bf16 v[2:5], v[162:165], v[218:221], v[2:5]
	v_mfma_f32_16x16x32_bf16 v[54:57], v[158:161], v[198:201], v[54:57]
	v_mfma_f32_16x16x32_bf16 v[50:53], v[190:193], v[198:201], v[50:53]
	v_mfma_f32_16x16x32_bf16 v[38:41], v[158:161], v[206:209], v[38:41]
	v_mfma_f32_16x16x32_bf16 v[34:37], v[190:193], v[206:209], v[34:37]
	v_mfma_f32_16x16x32_bf16 v[22:25], v[158:161], v[214:217], v[22:25]
	v_mfma_f32_16x16x32_bf16 v[18:21], v[190:193], v[214:217], v[18:21]
	v_mfma_f32_16x16x32_bf16 v[6:9], v[158:161], v[222:225], v[6:9]
	v_mfma_f32_16x16x32_bf16 v[2:5], v[190:193], v[222:225], v[2:5]
	s_setprio 0
	s_barrier
	s_add_i32 s93, s93, 2
	s_add_u32 s82, s82, 0x100
	s_addc_u32 s83, s83, 0
	s_add_u32 s91, s91, 0x100
	s_addc_u32 s92, s92, 0
	s_cmp_gt_u32 s93, 29
	s_cbranch_scc1 .Lpeel_exit_1

.Lpeel_exit_1:
	s_and_b64 vcc, exec, s[40:41]
	s_cbranch_vccz .LBB0_566
	s_barrier

.LBB0_578:
	s_ashr_i32 s47, s46, 31
	s_lshl_b64 s[24:25], s[46:47], 20
	s_add_u32 s58, s6, s24
	s_addc_u32 s59, s7, s25
	s_and_b64 s[24:25], s[4:5], exec
	s_cselect_b32 s30, s59, s11
	s_cselect_b32 s31, s58, s10
	s_ashr_i32 s41, s40, 31
	s_lshl_b64 s[24:25], s[40:41], 20
	v_readlane_b32 s12, v255, 48
	v_readlane_b32 s13, v255, 49
	s_add_u32 s60, s12, s24
	s_addc_u32 s61, s13, s25
	s_and_b64 s[24:25], s[4:5], exec
	s_cselect_b32 s41, s61, s35
	s_cselect_b32 s47, s60, s34
	s_add_u32 s78, s10, 0x80080
	s_addc_u32 s79, s11, 0
	s_add_u32 s88, s34, 0x100
	s_addc_u32 s89, s35, 0
	s_mov_b32 s90, -2
	s_waitcnt vmcnt(0)
	ds_read_b128 v[130:133], v1
	ds_read_b128 v[134:137], v1 offset:1024
	ds_read_b128 v[138:141], v1 offset:2048
	ds_read_b128 v[142:145], v1 offset:3072
	ds_read_b128 v[146:149], v206
	ds_read_b128 v[150:153], v206 offset:1024
	ds_read_b128 v[154:157], v206 offset:2048
	ds_read_b128 v[158:161], v206 offset:3072
	s_add_u32 s10, s78, 0xfff80080
	s_addc_u32 s11, s79, -1
	s_cmp_eq_u32 s90, 28
	s_cselect_b32 s35, s30, s11
	s_cselect_b32 s34, s31, s10
	s_cselect_b32 s11, s41, s89
	s_cselect_b32 s10, s47, s88
	v_lshl_add_u64 v[216:217], s[78:79], 0, v[184:185]
	s_add_i32 m0, s50, 0xc000
	ds_read_b128 v[162:165], v207
	ds_read_b128 v[166:169], v207 offset:1024
	ds_read_b128 v[170:173], v207 offset:2048
	ds_read_b128 v[192:195], v207 offset:3072
	ds_read_b128 v[196:199], v207 offset:4096
	ds_read_b128 v[200:203], v207 offset:5120
	ds_read_b128 v[208:211], v207 offset:6144
	ds_read_b128 v[212:215], v207 offset:7168
	global_load_lds_dwordx4 v[216:217], off
	v_lshl_add_u64 v[216:217], s[78:79], 0, v[186:187]
	s_add_i32 m0, s50, 0xe000
	s_nop 0
	global_load_lds_dwordx4 v[216:217], off
	s_waitcnt vmcnt(8)
	s_waitcnt lgkmcnt(0)
	s_barrier
	s_setprio 1
	s_waitcnt lgkmcnt(0)
	v_mfma_f32_16x16x32_bf16 v[126:129], v[130:133], v[162:165], 0
	v_mfma_f32_16x16x32_bf16 v[122:125], v[138:141], v[162:165], 0
	v_mfma_f32_16x16x32_bf16 v[110:113], v[130:133], v[170:173], 0
	v_mfma_f32_16x16x32_bf16 v[106:109], v[138:141], v[170:173], 0
	v_mfma_f32_16x16x32_bf16 v[94:97], v[130:133], v[196:199], 0
	v_mfma_f32_16x16x32_bf16 v[90:93], v[138:141], v[196:199], 0
	v_mfma_f32_16x16x32_bf16 v[78:81], v[130:133], v[208:211], 0
	v_mfma_f32_16x16x32_bf16 v[74:77], v[138:141], v[208:211], 0
	v_mfma_f32_16x16x32_bf16 v[126:129], v[134:137], v[166:169], v[126:129]
	v_mfma_f32_16x16x32_bf16 v[122:125], v[142:145], v[166:169], v[122:125]
	v_mfma_f32_16x16x32_bf16 v[110:113], v[134:137], v[192:195], v[110:113]
	v_mfma_f32_16x16x32_bf16 v[106:109], v[142:145], v[192:195], v[106:109]
	v_mfma_f32_16x16x32_bf16 v[94:97], v[134:137], v[200:203], v[94:97]
	v_mfma_f32_16x16x32_bf16 v[90:93], v[142:145], v[200:203], v[90:93]
	v_mfma_f32_16x16x32_bf16 v[78:81], v[134:137], v[212:215], v[78:81]
	v_mfma_f32_16x16x32_bf16 v[74:77], v[142:145], v[212:215], v[74:77]
	s_setprio 0
	s_setprio 1
	v_mfma_f32_16x16x32_bf16 v[118:121], v[146:149], v[162:165], 0
	v_mfma_f32_16x16x32_bf16 v[114:117], v[154:157], v[162:165], 0
	v_mfma_f32_16x16x32_bf16 v[102:105], v[146:149], v[170:173], 0
	v_mfma_f32_16x16x32_bf16 v[98:101], v[154:157], v[170:173], 0
	v_mfma_f32_16x16x32_bf16 v[86:89], v[146:149], v[196:199], 0
	v_mfma_f32_16x16x32_bf16 v[82:85], v[154:157], v[196:199], 0
	v_mfma_f32_16x16x32_bf16 v[70:73], v[146:149], v[208:211], 0
	v_mfma_f32_16x16x32_bf16 v[66:69], v[154:157], v[208:211], 0
	v_mfma_f32_16x16x32_bf16 v[118:121], v[150:153], v[166:169], v[118:121]
	v_mfma_f32_16x16x32_bf16 v[114:117], v[158:161], v[166:169], v[114:117]
	v_mfma_f32_16x16x32_bf16 v[102:105], v[150:153], v[192:195], v[102:105]
	v_mfma_f32_16x16x32_bf16 v[98:101], v[158:161], v[192:195], v[98:101]
	v_mfma_f32_16x16x32_bf16 v[86:89], v[150:153], v[200:203], v[86:89]
	v_mfma_f32_16x16x32_bf16 v[82:85], v[158:161], v[200:203], v[82:85]
	v_mfma_f32_16x16x32_bf16 v[70:73], v[150:153], v[212:215], v[70:73]
	v_mfma_f32_16x16x32_bf16 v[66:69], v[158:161], v[212:215], v[66:69]
	s_setprio 0
	s_barrier
	s_add_i32 s24, s84, s3
	v_lshl_add_u64 v[216:217], s[10:11], 0, v[178:179]
	s_mov_b32 m0, s24
	ds_read_b128 v[162:165], v207 offset:16384
	ds_read_b128 v[166:169], v207 offset:17408
	ds_read_b128 v[170:173], v207 offset:18432
	ds_read_b128 v[192:195], v207 offset:19456
	ds_read_b128 v[196:199], v207 offset:20480
	ds_read_b128 v[200:203], v207 offset:21504
	ds_read_b128 v[208:211], v207 offset:22528
	ds_read_b128 v[212:215], v207 offset:23552
	global_load_lds_dwordx4 v[216:217], off
	s_add_i32 m0, s24, 0x2000
	s_add_u32 s24, s10, 0x80000
	v_lshl_add_u64 v[218:219], s[10:11], 0, v[182:183]
	s_addc_u32 s25, s11, 0
	s_add_i32 s91, s85, s3
	global_load_lds_dwordx4 v[218:219], off
	v_lshl_add_u64 v[220:221], s[24:25], 0, v[178:179]
	s_mov_b32 m0, s91
	v_lshl_add_u64 v[222:223], s[34:35], 0, v[180:181]
	global_load_lds_dwordx4 v[220:221], off
	v_lshl_add_u64 v[220:221], s[24:25], 0, v[182:183]
	s_add_i32 m0, s91, 0x2000
	s_nop 0
	global_load_lds_dwordx4 v[220:221], off
	v_lshl_add_u64 v[220:221], s[34:35], 0, v[176:177]
	s_mov_b32 m0, s50
	s_nop 0
	global_load_lds_dwordx4 v[220:221], off
	s_mov_b32 m0, s51
	s_nop 0
	global_load_lds_dwordx4 v[222:223], off
	s_waitcnt vmcnt(8)
	s_waitcnt lgkmcnt(0)
	s_barrier
	s_setprio 1
	s_waitcnt lgkmcnt(0)
	v_mfma_f32_16x16x32_bf16 v[62:65], v[130:133], v[162:165], 0
	v_mfma_f32_16x16x32_bf16 v[58:61], v[138:141], v[162:165], 0
	v_mfma_f32_16x16x32_bf16 v[46:49], v[130:133], v[170:173], 0
	v_mfma_f32_16x16x32_bf16 v[42:45], v[138:141], v[170:173], 0
	v_mfma_f32_16x16x32_bf16 v[30:33], v[130:133], v[196:199], 0
	v_mfma_f32_16x16x32_bf16 v[26:29], v[138:141], v[196:199], 0
	v_mfma_f32_16x16x32_bf16 v[14:17], v[130:133], v[208:211], 0
	v_mfma_f32_16x16x32_bf16 v[10:13], v[138:141], v[208:211], 0
	v_mfma_f32_16x16x32_bf16 v[62:65], v[134:137], v[166:169], v[62:65]
	v_mfma_f32_16x16x32_bf16 v[58:61], v[142:145], v[166:169], v[58:61]
	v_mfma_f32_16x16x32_bf16 v[46:49], v[134:137], v[192:195], v[46:49]
	v_mfma_f32_16x16x32_bf16 v[42:45], v[142:145], v[192:195], v[42:45]
	v_mfma_f32_16x16x32_bf16 v[30:33], v[134:137], v[200:203], v[30:33]
	v_mfma_f32_16x16x32_bf16 v[26:29], v[142:145], v[200:203], v[26:29]
	v_mfma_f32_16x16x32_bf16 v[14:17], v[134:137], v[212:215], v[14:17]
	v_mfma_f32_16x16x32_bf16 v[10:13], v[142:145], v[212:215], v[10:13]
	s_setprio 0
	s_setprio 1
	v_mfma_f32_16x16x32_bf16 v[54:57], v[146:149], v[162:165], 0
	v_mfma_f32_16x16x32_bf16 v[50:53], v[154:157], v[162:165], 0
	v_mfma_f32_16x16x32_bf16 v[38:41], v[146:149], v[170:173], 0
	v_mfma_f32_16x16x32_bf16 v[34:37], v[154:157], v[170:173], 0
	v_mfma_f32_16x16x32_bf16 v[22:25], v[146:149], v[196:199], 0
	v_mfma_f32_16x16x32_bf16 v[18:21], v[154:157], v[196:199], 0
	v_mfma_f32_16x16x32_bf16 v[6:9], v[146:149], v[208:211], 0
	v_mfma_f32_16x16x32_bf16 v[2:5], v[154:157], v[208:211], 0
	v_mfma_f32_16x16x32_bf16 v[54:57], v[150:153], v[166:169], v[54:57]
	v_mfma_f32_16x16x32_bf16 v[50:53], v[158:161], v[166:169], v[50:53]
	v_mfma_f32_16x16x32_bf16 v[38:41], v[150:153], v[192:195], v[38:41]
	v_mfma_f32_16x16x32_bf16 v[34:37], v[158:161], v[192:195], v[34:37]
	v_mfma_f32_16x16x32_bf16 v[22:25], v[150:153], v[200:203], v[22:25]
	v_mfma_f32_16x16x32_bf16 v[18:21], v[158:161], v[200:203], v[18:21]
	v_mfma_f32_16x16x32_bf16 v[6:9], v[150:153], v[212:215], v[6:9]
	v_mfma_f32_16x16x32_bf16 v[2:5], v[158:161], v[212:215], v[2:5]
	s_setprio 0
	s_barrier
	s_add_i32 s91, 0, 0x18000
	s_add_i32 s92, 0, 0x1c000
	v_add_u32_e32 v142, s91, v175
	v_add_u32_e32 v158, s92, v175
	ds_read_b128 v[130:133], v142
	ds_read_b128 v[134:137], v142 offset:1024
	ds_read_b128 v[138:141], v142 offset:2048
	ds_read_b128 v[142:145], v142 offset:3072
	ds_read_b128 v[146:149], v158
	ds_read_b128 v[150:153], v158 offset:1024
	ds_read_b128 v[154:157], v158 offset:2048
	ds_read_b128 v[158:161], v158 offset:3072
	s_add_u32 s24, s34, 0x80000
	s_addc_u32 s25, s35, 0
	s_mov_b32 m0, s63
	v_lshl_add_u64 v[224:225], s[24:25], 0, v[176:177]
	ds_read_b128 v[162:165], v207 offset:32768
	ds_read_b128 v[166:169], v207 offset:33792
	ds_read_b128 v[170:173], v207 offset:34816
	ds_read_b128 v[192:195], v207 offset:35840
	ds_read_b128 v[196:199], v207 offset:36864
	ds_read_b128 v[200:203], v207 offset:37888
	ds_read_b128 v[208:211], v207 offset:38912
	ds_read_b128 v[212:215], v207 offset:39936
	global_load_lds_dwordx4 v[224:225], off
	v_lshl_add_u64 v[224:225], s[24:25], 0, v[180:181]
	s_mov_b32 m0, s75
	s_nop 0
	global_load_lds_dwordx4 v[224:225], off
	s_waitcnt vmcnt(8)
	s_waitcnt lgkmcnt(0)
	s_barrier
	s_setprio 1
	s_waitcnt lgkmcnt(0)
	v_mfma_f32_16x16x32_bf16 v[126:129], v[130:133], v[162:165], v[126:129]
	v_mfma_f32_16x16x32_bf16 v[122:125], v[138:141], v[162:165], v[122:125]
	v_mfma_f32_16x16x32_bf16 v[110:113], v[130:133], v[170:173], v[110:113]
	v_mfma_f32_16x16x32_bf16 v[106:109], v[138:141], v[170:173], v[106:109]
	v_mfma_f32_16x16x32_bf16 v[94:97], v[130:133], v[196:199], v[94:97]
	v_mfma_f32_16x16x32_bf16 v[90:93], v[138:141], v[196:199], v[90:93]
	v_mfma_f32_16x16x32_bf16 v[78:81], v[130:133], v[208:211], v[78:81]
	v_mfma_f32_16x16x32_bf16 v[74:77], v[138:141], v[208:211], v[74:77]
	v_mfma_f32_16x16x32_bf16 v[126:129], v[134:137], v[166:169], v[126:129]
	v_mfma_f32_16x16x32_bf16 v[122:125], v[142:145], v[166:169], v[122:125]
	v_mfma_f32_16x16x32_bf16 v[110:113], v[134:137], v[192:195], v[110:113]
	v_mfma_f32_16x16x32_bf16 v[106:109], v[142:145], v[192:195], v[106:109]
	v_mfma_f32_16x16x32_bf16 v[94:97], v[134:137], v[200:203], v[94:97]
	v_mfma_f32_16x16x32_bf16 v[90:93], v[142:145], v[200:203], v[90:93]
	v_mfma_f32_16x16x32_bf16 v[78:81], v[134:137], v[212:215], v[78:81]
	v_mfma_f32_16x16x32_bf16 v[74:77], v[142:145], v[212:215], v[74:77]
	s_setprio 0
	s_setprio 1
	v_mfma_f32_16x16x32_bf16 v[118:121], v[146:149], v[162:165], v[118:121]
	v_mfma_f32_16x16x32_bf16 v[114:117], v[154:157], v[162:165], v[114:117]
	v_mfma_f32_16x16x32_bf16 v[102:105], v[146:149], v[170:173], v[102:105]
	v_mfma_f32_16x16x32_bf16 v[98:101], v[154:157], v[170:173], v[98:101]
	v_mfma_f32_16x16x32_bf16 v[86:89], v[146:149], v[196:199], v[86:89]
	v_mfma_f32_16x16x32_bf16 v[82:85], v[154:157], v[196:199], v[82:85]
	v_mfma_f32_16x16x32_bf16 v[70:73], v[146:149], v[208:211], v[70:73]
	v_mfma_f32_16x16x32_bf16 v[66:69], v[154:157], v[208:211], v[66:69]
	v_mfma_f32_16x16x32_bf16 v[118:121], v[150:153], v[166:169], v[118:121]
	v_mfma_f32_16x16x32_bf16 v[114:117], v[158:161], v[166:169], v[114:117]
	v_mfma_f32_16x16x32_bf16 v[102:105], v[150:153], v[192:195], v[102:105]
	v_mfma_f32_16x16x32_bf16 v[98:101], v[158:161], v[192:195], v[98:101]
	v_mfma_f32_16x16x32_bf16 v[86:89], v[150:153], v[200:203], v[86:89]
	v_mfma_f32_16x16x32_bf16 v[82:85], v[158:161], v[200:203], v[82:85]
	v_mfma_f32_16x16x32_bf16 v[70:73], v[150:153], v[212:215], v[70:73]
	v_mfma_f32_16x16x32_bf16 v[66:69], v[158:161], v[212:215], v[66:69]
	s_setprio 0
	s_barrier
	s_add_i32 s24, s91, s3
	v_lshl_add_u64 v[216:217], v[216:217], 0, s[36:37]
	s_mov_b32 m0, s24
	ds_read_b128 v[162:165], v207 offset:49152
	ds_read_b128 v[166:169], v207 offset:50176
	ds_read_b128 v[170:173], v207 offset:51200
	ds_read_b128 v[192:195], v207 offset:52224
	ds_read_b128 v[196:199], v207 offset:53248
	ds_read_b128 v[200:203], v207 offset:54272
	ds_read_b128 v[208:211], v207 offset:55296
	ds_read_b128 v[212:215], v207 offset:56320
	global_load_lds_dwordx4 v[216:217], off
	s_add_i32 m0, s24, 0x2000
	s_add_u32 s10, s10, 0x80080
	v_lshl_add_u64 v[216:217], v[218:219], 0, s[36:37]
	s_addc_u32 s11, s11, 0
	s_add_i32 s24, s92, s3
	global_load_lds_dwordx4 v[216:217], off
	v_lshl_add_u64 v[216:217], s[10:11], 0, v[178:179]
	s_mov_b32 m0, s24
	s_nop 0
	global_load_lds_dwordx4 v[216:217], off
	v_lshl_add_u64 v[216:217], s[10:11], 0, v[182:183]
	s_add_i32 m0, s24, 0x2000
	s_nop 0
	global_load_lds_dwordx4 v[216:217], off
	v_lshl_add_u64 v[216:217], v[220:221], 0, s[36:37]
	s_mov_b32 m0, s81
	s_nop 0
	global_load_lds_dwordx4 v[216:217], off
	v_lshl_add_u64 v[216:217], v[222:223], 0, s[36:37]
	s_mov_b32 m0, s82
	s_nop 0
	global_load_lds_dwordx4 v[216:217], off
	s_waitcnt vmcnt(8)
	s_waitcnt lgkmcnt(0)
	s_barrier
	s_setprio 1
	s_waitcnt lgkmcnt(0)
	v_mfma_f32_16x16x32_bf16 v[62:65], v[130:133], v[162:165], v[62:65]
	v_mfma_f32_16x16x32_bf16 v[58:61], v[138:141], v[162:165], v[58:61]
	v_mfma_f32_16x16x32_bf16 v[46:49], v[130:133], v[170:173], v[46:49]
	v_mfma_f32_16x16x32_bf16 v[42:45], v[138:141], v[170:173], v[42:45]
	v_mfma_f32_16x16x32_bf16 v[30:33], v[130:133], v[196:199], v[30:33]
	v_mfma_f32_16x16x32_bf16 v[26:29], v[138:141], v[196:199], v[26:29]
	v_mfma_f32_16x16x32_bf16 v[14:17], v[130:133], v[208:211], v[14:17]
	v_mfma_f32_16x16x32_bf16 v[10:13], v[138:141], v[208:211], v[10:13]
	v_mfma_f32_16x16x32_bf16 v[62:65], v[134:137], v[166:169], v[62:65]
	v_mfma_f32_16x16x32_bf16 v[58:61], v[142:145], v[166:169], v[58:61]
	v_mfma_f32_16x16x32_bf16 v[46:49], v[134:137], v[192:195], v[46:49]
	v_mfma_f32_16x16x32_bf16 v[42:45], v[142:145], v[192:195], v[42:45]
	v_mfma_f32_16x16x32_bf16 v[30:33], v[134:137], v[200:203], v[30:33]
	v_mfma_f32_16x16x32_bf16 v[26:29], v[142:145], v[200:203], v[26:29]
	v_mfma_f32_16x16x32_bf16 v[14:17], v[134:137], v[212:215], v[14:17]
	v_mfma_f32_16x16x32_bf16 v[10:13], v[142:145], v[212:215], v[10:13]
	s_setprio 0
	s_setprio 1
	v_mfma_f32_16x16x32_bf16 v[54:57], v[146:149], v[162:165], v[54:57]
	v_mfma_f32_16x16x32_bf16 v[50:53], v[154:157], v[162:165], v[50:53]
	v_mfma_f32_16x16x32_bf16 v[38:41], v[146:149], v[170:173], v[38:41]
	v_mfma_f32_16x16x32_bf16 v[34:37], v[154:157], v[170:173], v[34:37]
	v_mfma_f32_16x16x32_bf16 v[22:25], v[146:149], v[196:199], v[22:25]
	v_mfma_f32_16x16x32_bf16 v[18:21], v[154:157], v[196:199], v[18:21]
	v_mfma_f32_16x16x32_bf16 v[6:9], v[146:149], v[208:211], v[6:9]
	v_mfma_f32_16x16x32_bf16 v[2:5], v[154:157], v[208:211], v[2:5]
	v_mfma_f32_16x16x32_bf16 v[54:57], v[150:153], v[166:169], v[54:57]
	v_mfma_f32_16x16x32_bf16 v[50:53], v[158:161], v[166:169], v[50:53]
	v_mfma_f32_16x16x32_bf16 v[38:41], v[150:153], v[192:195], v[38:41]
	v_mfma_f32_16x16x32_bf16 v[34:37], v[158:161], v[192:195], v[34:37]
	v_mfma_f32_16x16x32_bf16 v[22:25], v[150:153], v[200:203], v[22:25]
	v_mfma_f32_16x16x32_bf16 v[18:21], v[158:161], v[200:203], v[18:21]
	v_mfma_f32_16x16x32_bf16 v[6:9], v[150:153], v[212:215], v[6:9]
	v_mfma_f32_16x16x32_bf16 v[2:5], v[158:161], v[212:215], v[2:5]
	s_setprio 0
	s_barrier
	s_add_i32 s90, s90, 2
	s_add_u32 s78, s78, 0x100
	s_addc_u32 s79, s79, 0
	s_add_u32 s88, s88, 0x100
	s_addc_u32 s89, s89, 0
	s_cmp_gt_u32 s90, 29
	s_cbranch_scc1 .Lpeel_exit_2

.Lpeel_exit_2:
	s_and_b64 vcc, exec, s[38:39]
	s_cbranch_vccz .LBB0_582
	s_barrier

.LBB0_649:
	s_ashr_i32 s47, s46, 31
	s_lshl_b64 s[10:11], s[46:47], 21
	s_add_u32 s48, s76, s10
	s_addc_u32 s49, s77, s11
	s_and_b64 s[10:11], s[4:5], exec
	s_cselect_b32 s47, s49, s61
	s_cselect_b32 s85, s48, s60
	s_ashr_i32 s45, s44, 31
	s_lshl_b64 s[10:11], s[44:45], 21
	v_readlane_b32 s12, v255, 50
	v_readlane_b32 s13, v255, 51
	s_add_u32 s56, s12, s10
	s_addc_u32 s57, s13, s11
	s_and_b64 s[10:11], s[4:5], exec
	s_cselect_b32 s45, s57, s35
	s_cselect_b32 s86, s56, s34
	s_add_u32 s60, s60, 0x100080
	s_addc_u32 s61, s61, 0
	s_add_u32 s87, s34, 0x100
	s_addc_u32 s88, s35, 0
	s_mov_b32 s89, -2
	ds_read_b128 v[154:157], v150
	ds_read_b128 v[158:161], v150 offset:1024
	ds_read_b128 v[162:165], v150 offset:2048
	ds_read_b128 v[166:169], v150 offset:3072
	ds_read_b128 v[170:173], v151
	ds_read_b128 v[176:179], v151 offset:1024
	ds_read_b128 v[180:183], v151 offset:2048
	ds_read_b128 v[184:187], v151 offset:3072
	s_add_u32 s10, s60, 0xfff00080
	s_addc_u32 s11, s61, -1
	s_cmp_eq_u32 s89, 60
	s_cselect_b32 s35, s47, s11
	s_cselect_b32 s34, s85, s10
	s_cselect_b32 s11, s45, s88
	s_cselect_b32 s10, s86, s87
	v_lshl_add_u64 v[146:147], s[60:61], 0, v[138:139]
	s_add_i32 m0, s50, 0xc000
	ds_read_b128 v[188:191], v152
	ds_read_b128 v[192:195], v152 offset:1024
	ds_read_b128 v[196:199], v152 offset:2048
	ds_read_b128 v[200:203], v152 offset:3072
	ds_read_b128 v[204:207], v152 offset:4096
	ds_read_b128 v[208:211], v152 offset:5120
	ds_read_b128 v[212:215], v152 offset:6144
	ds_read_b128 v[216:219], v152 offset:7168
	global_load_lds_dwordx4 v[146:147], off
	v_lshl_add_u64 v[146:147], s[60:61], 0, v[140:141]
	s_add_i32 m0, s50, 0xe000
	s_nop 0
	global_load_lds_dwordx4 v[146:147], off
	s_waitcnt vmcnt(8)
	s_waitcnt lgkmcnt(0)
	s_barrier
	s_setprio 1
	s_waitcnt lgkmcnt(0)
	v_mfma_f32_16x16x32_bf16 v[126:129], v[154:157], v[188:191], 0
	v_mfma_f32_16x16x32_bf16 v[122:125], v[162:165], v[188:191], 0
	v_mfma_f32_16x16x32_bf16 v[114:117], v[154:157], v[196:199], 0
	v_mfma_f32_16x16x32_bf16 v[106:109], v[162:165], v[196:199], 0
	v_mfma_f32_16x16x32_bf16 v[98:101], v[154:157], v[204:207], 0
	v_mfma_f32_16x16x32_bf16 v[90:93], v[162:165], v[204:207], 0
	v_mfma_f32_16x16x32_bf16 v[82:85], v[154:157], v[212:215], 0
	v_mfma_f32_16x16x32_bf16 v[74:77], v[162:165], v[212:215], 0
	v_mfma_f32_16x16x32_bf16 v[126:129], v[158:161], v[192:195], v[126:129]
	v_mfma_f32_16x16x32_bf16 v[122:125], v[166:169], v[192:195], v[122:125]
	v_mfma_f32_16x16x32_bf16 v[114:117], v[158:161], v[200:203], v[114:117]
	v_mfma_f32_16x16x32_bf16 v[106:109], v[166:169], v[200:203], v[106:109]
	v_mfma_f32_16x16x32_bf16 v[98:101], v[158:161], v[208:211], v[98:101]
	v_mfma_f32_16x16x32_bf16 v[90:93], v[166:169], v[208:211], v[90:93]
	v_mfma_f32_16x16x32_bf16 v[82:85], v[158:161], v[216:219], v[82:85]
	v_mfma_f32_16x16x32_bf16 v[74:77], v[166:169], v[216:219], v[74:77]
	s_setprio 0
	s_setprio 1
	v_mfma_f32_16x16x32_bf16 v[118:121], v[170:173], v[188:191], 0
	v_mfma_f32_16x16x32_bf16 v[110:113], v[180:183], v[188:191], 0
	v_mfma_f32_16x16x32_bf16 v[102:105], v[170:173], v[196:199], 0
	v_mfma_f32_16x16x32_bf16 v[94:97], v[180:183], v[196:199], 0
	v_mfma_f32_16x16x32_bf16 v[86:89], v[170:173], v[204:207], 0
	v_mfma_f32_16x16x32_bf16 v[78:81], v[180:183], v[204:207], 0
	v_mfma_f32_16x16x32_bf16 v[70:73], v[170:173], v[212:215], 0
	v_mfma_f32_16x16x32_bf16 v[66:69], v[180:183], v[212:215], 0
	v_mfma_f32_16x16x32_bf16 v[118:121], v[176:179], v[192:195], v[118:121]
	v_mfma_f32_16x16x32_bf16 v[110:113], v[184:187], v[192:195], v[110:113]
	v_mfma_f32_16x16x32_bf16 v[102:105], v[176:179], v[200:203], v[102:105]
	v_mfma_f32_16x16x32_bf16 v[94:97], v[184:187], v[200:203], v[94:97]
	v_mfma_f32_16x16x32_bf16 v[86:89], v[176:179], v[208:211], v[86:89]
	v_mfma_f32_16x16x32_bf16 v[78:81], v[184:187], v[208:211], v[78:81]
	v_mfma_f32_16x16x32_bf16 v[70:73], v[176:179], v[216:219], v[70:73]
	v_mfma_f32_16x16x32_bf16 v[66:69], v[184:187], v[216:219], v[66:69]
	s_setprio 0
	s_barrier
	s_add_i32 s24, s80, s3
	v_lshl_add_u64 v[146:147], s[10:11], 0, v[134:135]
	s_mov_b32 m0, s24
	ds_read_b128 v[188:191], v152 offset:16384
	ds_read_b128 v[192:195], v152 offset:17408
	ds_read_b128 v[196:199], v152 offset:18432
	ds_read_b128 v[200:203], v152 offset:19456
	ds_read_b128 v[204:207], v152 offset:20480
	ds_read_b128 v[208:211], v152 offset:21504
	ds_read_b128 v[212:215], v152 offset:22528
	ds_read_b128 v[216:219], v152 offset:23552
	global_load_lds_dwordx4 v[146:147], off
	s_add_i32 m0, s24, 0x2000
	s_add_u32 s24, s10, 0x100000
	v_lshl_add_u64 v[220:221], s[10:11], 0, v[130:131]
	s_addc_u32 s25, s11, 0
	s_add_i32 s90, s81, s3
	global_load_lds_dwordx4 v[220:221], off
	v_lshl_add_u64 v[222:223], s[24:25], 0, v[134:135]
	s_mov_b32 m0, s90
	v_lshl_add_u64 v[224:225], s[34:35], 0, v[132:133]
	global_load_lds_dwordx4 v[222:223], off
	v_lshl_add_u64 v[222:223], s[24:25], 0, v[130:131]
	s_add_i32 m0, s90, 0x2000
	s_nop 0
	global_load_lds_dwordx4 v[222:223], off
	v_lshl_add_u64 v[222:223], s[34:35], 0, v[136:137]
	s_mov_b32 m0, s50
	s_nop 0
	global_load_lds_dwordx4 v[222:223], off
	s_mov_b32 m0, s51
	s_nop 0
	global_load_lds_dwordx4 v[224:225], off
	s_waitcnt vmcnt(8)
	s_waitcnt lgkmcnt(0)
	s_barrier
	s_setprio 1
	s_waitcnt lgkmcnt(0)
	v_mfma_f32_16x16x32_bf16 v[62:65], v[154:157], v[188:191], 0
	v_mfma_f32_16x16x32_bf16 v[58:61], v[162:165], v[188:191], 0
	v_mfma_f32_16x16x32_bf16 v[50:53], v[154:157], v[196:199], 0
	v_mfma_f32_16x16x32_bf16 v[42:45], v[162:165], v[196:199], 0
	v_mfma_f32_16x16x32_bf16 v[34:37], v[154:157], v[204:207], 0
	v_mfma_f32_16x16x32_bf16 v[26:29], v[162:165], v[204:207], 0
	v_mfma_f32_16x16x32_bf16 v[18:21], v[154:157], v[212:215], 0
	v_mfma_f32_16x16x32_bf16 v[10:13], v[162:165], v[212:215], 0
	v_mfma_f32_16x16x32_bf16 v[62:65], v[158:161], v[192:195], v[62:65]
	v_mfma_f32_16x16x32_bf16 v[58:61], v[166:169], v[192:195], v[58:61]
	v_mfma_f32_16x16x32_bf16 v[50:53], v[158:161], v[200:203], v[50:53]
	v_mfma_f32_16x16x32_bf16 v[42:45], v[166:169], v[200:203], v[42:45]
	v_mfma_f32_16x16x32_bf16 v[34:37], v[158:161], v[208:211], v[34:37]
	v_mfma_f32_16x16x32_bf16 v[26:29], v[166:169], v[208:211], v[26:29]
	v_mfma_f32_16x16x32_bf16 v[18:21], v[158:161], v[216:219], v[18:21]
	v_mfma_f32_16x16x32_bf16 v[10:13], v[166:169], v[216:219], v[10:13]
	s_setprio 0
	s_setprio 1
	v_mfma_f32_16x16x32_bf16 v[54:57], v[170:173], v[188:191], 0
	v_mfma_f32_16x16x32_bf16 v[46:49], v[180:183], v[188:191], 0
	v_mfma_f32_16x16x32_bf16 v[38:41], v[170:173], v[196:199], 0
	v_mfma_f32_16x16x32_bf16 v[30:33], v[180:183], v[196:199], 0
	v_mfma_f32_16x16x32_bf16 v[22:25], v[170:173], v[204:207], 0
	v_mfma_f32_16x16x32_bf16 v[14:17], v[180:183], v[204:207], 0
	v_mfma_f32_16x16x32_bf16 v[6:9], v[170:173], v[212:215], 0
	v_mfma_f32_16x16x32_bf16 v[2:5], v[180:183], v[212:215], 0
	v_mfma_f32_16x16x32_bf16 v[54:57], v[176:179], v[192:195], v[54:57]
	v_mfma_f32_16x16x32_bf16 v[46:49], v[184:187], v[192:195], v[46:49]
	v_mfma_f32_16x16x32_bf16 v[38:41], v[176:179], v[200:203], v[38:41]
	v_mfma_f32_16x16x32_bf16 v[30:33], v[184:187], v[200:203], v[30:33]
	v_mfma_f32_16x16x32_bf16 v[22:25], v[176:179], v[208:211], v[22:25]
	v_mfma_f32_16x16x32_bf16 v[14:17], v[184:187], v[208:211], v[14:17]
	v_mfma_f32_16x16x32_bf16 v[6:9], v[176:179], v[216:219], v[6:9]
	v_mfma_f32_16x16x32_bf16 v[2:5], v[184:187], v[216:219], v[2:5]
	s_setprio 0
	s_barrier
	s_add_i32 s90, 0, 0x18000
	v_add_u32_e32 v153, s90, v148
	s_add_i32 s91, 0, 0x1c000
	ds_read_b128 v[154:157], v153
	ds_read_b128 v[158:161], v153 offset:1024
	ds_read_b128 v[162:165], v153 offset:2048
	ds_read_b128 v[166:169], v153 offset:3072
	v_add_u32_e32 v153, s91, v148
	ds_read_b128 v[170:173], v153
	ds_read_b128 v[176:179], v153 offset:1024
	ds_read_b128 v[180:183], v153 offset:2048
	ds_read_b128 v[184:187], v153 offset:3072
	s_add_u32 s24, s34, 0x100000
	s_addc_u32 s25, s35, 0
	s_mov_b32 m0, s59
	v_lshl_add_u64 v[226:227], s[24:25], 0, v[136:137]
	ds_read_b128 v[188:191], v152 offset:32768
	ds_read_b128 v[192:195], v152 offset:33792
	ds_read_b128 v[196:199], v152 offset:34816
	ds_read_b128 v[200:203], v152 offset:35840
	ds_read_b128 v[204:207], v152 offset:36864
	ds_read_b128 v[208:211], v152 offset:37888
	ds_read_b128 v[212:215], v152 offset:38912
	ds_read_b128 v[216:219], v152 offset:39936
	global_load_lds_dwordx4 v[226:227], off
	v_lshl_add_u64 v[226:227], s[24:25], 0, v[132:133]
	s_mov_b32 m0, s62
	s_nop 0
	global_load_lds_dwordx4 v[226:227], off
	s_waitcnt vmcnt(8)
	s_waitcnt lgkmcnt(0)
	s_barrier
	s_setprio 1
	s_waitcnt lgkmcnt(0)
	v_mfma_f32_16x16x32_bf16 v[126:129], v[154:157], v[188:191], v[126:129]
	v_mfma_f32_16x16x32_bf16 v[122:125], v[162:165], v[188:191], v[122:125]
	v_mfma_f32_16x16x32_bf16 v[114:117], v[154:157], v[196:199], v[114:117]
	v_mfma_f32_16x16x32_bf16 v[106:109], v[162:165], v[196:199], v[106:109]
	v_mfma_f32_16x16x32_bf16 v[98:101], v[154:157], v[204:207], v[98:101]
	v_mfma_f32_16x16x32_bf16 v[90:93], v[162:165], v[204:207], v[90:93]
	v_mfma_f32_16x16x32_bf16 v[82:85], v[154:157], v[212:215], v[82:85]
	v_mfma_f32_16x16x32_bf16 v[74:77], v[162:165], v[212:215], v[74:77]
	v_mfma_f32_16x16x32_bf16 v[126:129], v[158:161], v[192:195], v[126:129]
	v_mfma_f32_16x16x32_bf16 v[122:125], v[166:169], v[192:195], v[122:125]
	v_mfma_f32_16x16x32_bf16 v[114:117], v[158:161], v[200:203], v[114:117]
	v_mfma_f32_16x16x32_bf16 v[106:109], v[166:169], v[200:203], v[106:109]
	v_mfma_f32_16x16x32_bf16 v[98:101], v[158:161], v[208:211], v[98:101]
	v_mfma_f32_16x16x32_bf16 v[90:93], v[166:169], v[208:211], v[90:93]
	v_mfma_f32_16x16x32_bf16 v[82:85], v[158:161], v[216:219], v[82:85]
	v_mfma_f32_16x16x32_bf16 v[74:77], v[166:169], v[216:219], v[74:77]
	s_setprio 0
	s_setprio 1
	v_mfma_f32_16x16x32_bf16 v[118:121], v[170:173], v[188:191], v[118:121]
	v_mfma_f32_16x16x32_bf16 v[110:113], v[180:183], v[188:191], v[110:113]
	v_mfma_f32_16x16x32_bf16 v[102:105], v[170:173], v[196:199], v[102:105]
	v_mfma_f32_16x16x32_bf16 v[94:97], v[180:183], v[196:199], v[94:97]
	v_mfma_f32_16x16x32_bf16 v[86:89], v[170:173], v[204:207], v[86:89]
	v_mfma_f32_16x16x32_bf16 v[78:81], v[180:183], v[204:207], v[78:81]
	v_mfma_f32_16x16x32_bf16 v[70:73], v[170:173], v[212:215], v[70:73]
	v_mfma_f32_16x16x32_bf16 v[66:69], v[180:183], v[212:215], v[66:69]
	v_mfma_f32_16x16x32_bf16 v[118:121], v[176:179], v[192:195], v[118:121]
	v_mfma_f32_16x16x32_bf16 v[110:113], v[184:187], v[192:195], v[110:113]
	v_mfma_f32_16x16x32_bf16 v[102:105], v[176:179], v[200:203], v[102:105]
	v_mfma_f32_16x16x32_bf16 v[94:97], v[184:187], v[200:203], v[94:97]
	v_mfma_f32_16x16x32_bf16 v[86:89], v[176:179], v[208:211], v[86:89]
	v_mfma_f32_16x16x32_bf16 v[78:81], v[184:187], v[208:211], v[78:81]
	v_mfma_f32_16x16x32_bf16 v[70:73], v[176:179], v[216:219], v[70:73]
	v_mfma_f32_16x16x32_bf16 v[66:69], v[184:187], v[216:219], v[66:69]
	s_setprio 0
	s_barrier
	s_add_i32 s24, s90, s3
	v_lshl_add_u64 v[146:147], v[146:147], 0, s[26:27]
	s_mov_b32 m0, s24
	ds_read_b128 v[188:191], v152 offset:49152
	ds_read_b128 v[192:195], v152 offset:50176
	ds_read_b128 v[196:199], v152 offset:51200
	ds_read_b128 v[200:203], v152 offset:52224
	ds_read_b128 v[204:207], v152 offset:53248
	ds_read_b128 v[208:211], v152 offset:54272
	ds_read_b128 v[212:215], v152 offset:55296
	ds_read_b128 v[216:219], v152 offset:56320
	global_load_lds_dwordx4 v[146:147], off
	s_add_i32 m0, s24, 0x2000
	s_add_u32 s10, s10, 0x100080
	v_lshl_add_u64 v[146:147], v[220:221], 0, s[26:27]
	s_addc_u32 s11, s11, 0
	s_add_i32 s24, s91, s3
	global_load_lds_dwordx4 v[146:147], off
	v_lshl_add_u64 v[146:147], s[10:11], 0, v[134:135]
	s_mov_b32 m0, s24
	s_nop 0
	global_load_lds_dwordx4 v[146:147], off
	v_lshl_add_u64 v[146:147], s[10:11], 0, v[130:131]
	s_add_i32 m0, s24, 0x2000
	s_nop 0
	global_load_lds_dwordx4 v[146:147], off
	v_lshl_add_u64 v[146:147], v[222:223], 0, s[26:27]
	s_mov_b32 m0, s75
	s_nop 0
	global_load_lds_dwordx4 v[146:147], off
	v_lshl_add_u64 v[146:147], v[224:225], 0, s[26:27]
	s_mov_b32 m0, s78
	s_nop 0
	global_load_lds_dwordx4 v[146:147], off
	s_waitcnt vmcnt(8)
	s_waitcnt lgkmcnt(0)
	s_barrier
	s_setprio 1
	s_waitcnt lgkmcnt(0)
	v_mfma_f32_16x16x32_bf16 v[62:65], v[154:157], v[188:191], v[62:65]
	v_mfma_f32_16x16x32_bf16 v[58:61], v[162:165], v[188:191], v[58:61]
	v_mfma_f32_16x16x32_bf16 v[50:53], v[154:157], v[196:199], v[50:53]
	v_mfma_f32_16x16x32_bf16 v[42:45], v[162:165], v[196:199], v[42:45]
	v_mfma_f32_16x16x32_bf16 v[34:37], v[154:157], v[204:207], v[34:37]
	v_mfma_f32_16x16x32_bf16 v[26:29], v[162:165], v[204:207], v[26:29]
	v_mfma_f32_16x16x32_bf16 v[18:21], v[154:157], v[212:215], v[18:21]
	v_mfma_f32_16x16x32_bf16 v[10:13], v[162:165], v[212:215], v[10:13]
	v_mfma_f32_16x16x32_bf16 v[62:65], v[158:161], v[192:195], v[62:65]
	v_mfma_f32_16x16x32_bf16 v[58:61], v[166:169], v[192:195], v[58:61]
	v_mfma_f32_16x16x32_bf16 v[50:53], v[158:161], v[200:203], v[50:53]
	v_mfma_f32_16x16x32_bf16 v[42:45], v[166:169], v[200:203], v[42:45]
	v_mfma_f32_16x16x32_bf16 v[34:37], v[158:161], v[208:211], v[34:37]
	v_mfma_f32_16x16x32_bf16 v[26:29], v[166:169], v[208:211], v[26:29]
	v_mfma_f32_16x16x32_bf16 v[18:21], v[158:161], v[216:219], v[18:21]
	v_mfma_f32_16x16x32_bf16 v[10:13], v[166:169], v[216:219], v[10:13]
	s_setprio 0
	s_setprio 1
	v_mfma_f32_16x16x32_bf16 v[54:57], v[170:173], v[188:191], v[54:57]
	v_mfma_f32_16x16x32_bf16 v[46:49], v[180:183], v[188:191], v[46:49]
	v_mfma_f32_16x16x32_bf16 v[38:41], v[170:173], v[196:199], v[38:41]
	v_mfma_f32_16x16x32_bf16 v[30:33], v[180:183], v[196:199], v[30:33]
	v_mfma_f32_16x16x32_bf16 v[22:25], v[170:173], v[204:207], v[22:25]
	v_mfma_f32_16x16x32_bf16 v[14:17], v[180:183], v[204:207], v[14:17]
	v_mfma_f32_16x16x32_bf16 v[6:9], v[170:173], v[212:215], v[6:9]
	v_mfma_f32_16x16x32_bf16 v[2:5], v[180:183], v[212:215], v[2:5]
	v_mfma_f32_16x16x32_bf16 v[54:57], v[176:179], v[192:195], v[54:57]
	v_mfma_f32_16x16x32_bf16 v[46:49], v[184:187], v[192:195], v[46:49]
	v_mfma_f32_16x16x32_bf16 v[38:41], v[176:179], v[200:203], v[38:41]
	v_mfma_f32_16x16x32_bf16 v[30:33], v[184:187], v[200:203], v[30:33]
	v_mfma_f32_16x16x32_bf16 v[22:25], v[176:179], v[208:211], v[22:25]
	v_mfma_f32_16x16x32_bf16 v[14:17], v[184:187], v[208:211], v[14:17]
	v_mfma_f32_16x16x32_bf16 v[6:9], v[176:179], v[216:219], v[6:9]
	v_mfma_f32_16x16x32_bf16 v[2:5], v[184:187], v[216:219], v[2:5]
	s_setprio 0
	s_barrier
	s_add_i32 s89, s89, 2
	s_add_u32 s60, s60, 0x100
	s_addc_u32 s61, s61, 0
	s_add_u32 s87, s87, 0x100
	s_addc_u32 s88, s88, 0
	s_cmp_gt_u32 s89, 61
	s_cbranch_scc1 .Lpeel_exit_3

.Lpeel_exit_3:
	s_and_b64 vcc, exec, s[36:37]
	s_cbranch_vccz .LBB0_653
	s_barrier

.LBB0_779:
	s_ashr_i32 s37, s36, 31
	s_lshl_b64 s[10:11], s[36:37], 21
	s_add_u32 s38, s42, s10
	s_addc_u32 s39, s43, s11
	s_and_b64 s[10:11], s[4:5], exec
	s_cselect_b32 s37, s39, s47
	s_cselect_b32 s78, s38, s46
	s_ashr_i32 s27, s26, 31
	s_lshl_b64 s[10:11], s[26:27], 21
	v_readlane_b32 s12, v255, 39
	v_readlane_b32 s13, v255, 40
	s_add_u32 s40, s12, s10
	s_addc_u32 s41, s13, s11
	s_and_b64 s[10:11], s[4:5], exec
	s_cselect_b32 s27, s41, s35
	s_cselect_b32 s79, s40, s34
	s_add_u32 s46, s46, 0x100080
	s_addc_u32 s47, s47, 0
	s_add_u32 s80, s34, 0x100
	s_addc_u32 s81, s35, 0
	s_mov_b32 s82, -2
	ds_read_b128 v[156:159], v152
	ds_read_b128 v[160:163], v152 offset:1024
	ds_read_b128 v[164:167], v152 offset:2048
	ds_read_b128 v[168:171], v152 offset:3072
	ds_read_b128 v[176:179], v153
	ds_read_b128 v[180:183], v153 offset:1024
	ds_read_b128 v[184:187], v153 offset:2048
	ds_read_b128 v[188:191], v153 offset:3072
	s_add_u32 s10, s46, 0xfff00080
	s_addc_u32 s11, s47, -1
	s_cmp_eq_u32 s82, 60
	s_cselect_b32 s35, s37, s11
	s_cselect_b32 s34, s78, s10
	s_cselect_b32 s11, s27, s81
	s_cselect_b32 s10, s79, s80
	v_lshl_add_u64 v[146:147], s[46:47], 0, v[138:139]
	s_add_i32 m0, s45, 0xc000
	ds_read_b128 v[192:195], v154
	ds_read_b128 v[196:199], v154 offset:1024
	ds_read_b128 v[200:203], v154 offset:2048
	ds_read_b128 v[204:207], v154 offset:3072
	ds_read_b128 v[208:211], v154 offset:4096
	ds_read_b128 v[212:215], v154 offset:5120
	ds_read_b128 v[216:219], v154 offset:6144
	ds_read_b128 v[220:223], v154 offset:7168
	global_load_lds_dwordx4 v[146:147], off
	v_lshl_add_u64 v[146:147], s[46:47], 0, v[140:141]
	s_add_i32 m0, s45, 0xe000
	s_nop 0
	global_load_lds_dwordx4 v[146:147], off
	s_waitcnt vmcnt(8)
	s_waitcnt lgkmcnt(0)
	s_barrier
	s_setprio 1
	s_waitcnt lgkmcnt(0)
	v_mfma_f32_16x16x32_bf16 v[126:129], v[156:159], v[192:195], 0
	v_mfma_f32_16x16x32_bf16 v[118:121], v[164:167], v[192:195], 0
	v_mfma_f32_16x16x32_bf16 v[110:113], v[156:159], v[200:203], 0
	v_mfma_f32_16x16x32_bf16 v[102:105], v[164:167], v[200:203], 0
	v_mfma_f32_16x16x32_bf16 v[94:97], v[156:159], v[208:211], 0
	v_mfma_f32_16x16x32_bf16 v[86:89], v[164:167], v[208:211], 0
	v_mfma_f32_16x16x32_bf16 v[78:81], v[156:159], v[216:219], 0
	v_mfma_f32_16x16x32_bf16 v[70:73], v[164:167], v[216:219], 0
	v_mfma_f32_16x16x32_bf16 v[126:129], v[160:163], v[196:199], v[126:129]
	v_mfma_f32_16x16x32_bf16 v[118:121], v[168:171], v[196:199], v[118:121]
	v_mfma_f32_16x16x32_bf16 v[110:113], v[160:163], v[204:207], v[110:113]
	v_mfma_f32_16x16x32_bf16 v[102:105], v[168:171], v[204:207], v[102:105]
	v_mfma_f32_16x16x32_bf16 v[94:97], v[160:163], v[212:215], v[94:97]
	v_mfma_f32_16x16x32_bf16 v[86:89], v[168:171], v[212:215], v[86:89]
	v_mfma_f32_16x16x32_bf16 v[78:81], v[160:163], v[220:223], v[78:81]
	v_mfma_f32_16x16x32_bf16 v[70:73], v[168:171], v[220:223], v[70:73]
	s_setprio 0
	s_setprio 1
	v_mfma_f32_16x16x32_bf16 v[122:125], v[176:179], v[192:195], 0
	v_mfma_f32_16x16x32_bf16 v[114:117], v[184:187], v[192:195], 0
	v_mfma_f32_16x16x32_bf16 v[106:109], v[176:179], v[200:203], 0
	v_mfma_f32_16x16x32_bf16 v[98:101], v[184:187], v[200:203], 0
	v_mfma_f32_16x16x32_bf16 v[90:93], v[176:179], v[208:211], 0
	v_mfma_f32_16x16x32_bf16 v[82:85], v[184:187], v[208:211], 0
	v_mfma_f32_16x16x32_bf16 v[74:77], v[176:179], v[216:219], 0
	v_mfma_f32_16x16x32_bf16 v[66:69], v[184:187], v[216:219], 0
	v_mfma_f32_16x16x32_bf16 v[122:125], v[180:183], v[196:199], v[122:125]
	v_mfma_f32_16x16x32_bf16 v[114:117], v[188:191], v[196:199], v[114:117]
	v_mfma_f32_16x16x32_bf16 v[106:109], v[180:183], v[204:207], v[106:109]
	v_mfma_f32_16x16x32_bf16 v[98:101], v[188:191], v[204:207], v[98:101]
	v_mfma_f32_16x16x32_bf16 v[90:93], v[180:183], v[212:215], v[90:93]
	v_mfma_f32_16x16x32_bf16 v[82:85], v[188:191], v[212:215], v[82:85]
	v_mfma_f32_16x16x32_bf16 v[74:77], v[180:183], v[220:223], v[74:77]
	v_mfma_f32_16x16x32_bf16 v[66:69], v[188:191], v[220:223], v[66:69]
	s_setprio 0
	s_barrier
	s_add_i32 s83, s55, s3
	v_lshl_add_u64 v[146:147], s[10:11], 0, v[134:135]
	s_mov_b32 m0, s83
	ds_read_b128 v[192:195], v154 offset:16384
	ds_read_b128 v[196:199], v154 offset:17408
	ds_read_b128 v[200:203], v154 offset:18432
	ds_read_b128 v[204:207], v154 offset:19456
	ds_read_b128 v[208:211], v154 offset:20480
	ds_read_b128 v[212:215], v154 offset:21504
	ds_read_b128 v[216:219], v154 offset:22528
	ds_read_b128 v[220:223], v154 offset:23552
	global_load_lds_dwordx4 v[146:147], off
	s_add_i32 m0, s83, 0x2000
	s_add_u32 s84, s10, 0x100000
	v_lshl_add_u64 v[172:173], s[10:11], 0, v[130:131]
	s_addc_u32 s85, s11, 0
	s_add_i32 s83, s56, s3
	global_load_lds_dwordx4 v[172:173], off
	v_lshl_add_u64 v[224:225], s[84:85], 0, v[134:135]
	s_mov_b32 m0, s83
	v_lshl_add_u64 v[226:227], s[34:35], 0, v[132:133]
	global_load_lds_dwordx4 v[224:225], off
	v_lshl_add_u64 v[224:225], s[84:85], 0, v[130:131]
	s_add_i32 m0, s83, 0x2000
	s_nop 0
	global_load_lds_dwordx4 v[224:225], off
	v_lshl_add_u64 v[224:225], s[34:35], 0, v[136:137]
	s_mov_b32 m0, s45
	s_nop 0
	global_load_lds_dwordx4 v[224:225], off
	s_mov_b32 m0, s48
	s_nop 0
	global_load_lds_dwordx4 v[226:227], off
	s_waitcnt vmcnt(8)
	s_waitcnt lgkmcnt(0)
	s_barrier
	s_setprio 1
	s_waitcnt lgkmcnt(0)
	v_mfma_f32_16x16x32_bf16 v[62:65], v[156:159], v[192:195], 0
	v_mfma_f32_16x16x32_bf16 v[54:57], v[164:167], v[192:195], 0
	v_mfma_f32_16x16x32_bf16 v[46:49], v[156:159], v[200:203], 0
	v_mfma_f32_16x16x32_bf16 v[38:41], v[164:167], v[200:203], 0
	v_mfma_f32_16x16x32_bf16 v[30:33], v[156:159], v[208:211], 0
	v_mfma_f32_16x16x32_bf16 v[22:25], v[164:167], v[208:211], 0
	v_mfma_f32_16x16x32_bf16 v[14:17], v[156:159], v[216:219], 0
	v_mfma_f32_16x16x32_bf16 v[6:9], v[164:167], v[216:219], 0
	v_mfma_f32_16x16x32_bf16 v[62:65], v[160:163], v[196:199], v[62:65]
	v_mfma_f32_16x16x32_bf16 v[54:57], v[168:171], v[196:199], v[54:57]
	v_mfma_f32_16x16x32_bf16 v[46:49], v[160:163], v[204:207], v[46:49]
	v_mfma_f32_16x16x32_bf16 v[38:41], v[168:171], v[204:207], v[38:41]
	v_mfma_f32_16x16x32_bf16 v[30:33], v[160:163], v[212:215], v[30:33]
	v_mfma_f32_16x16x32_bf16 v[22:25], v[168:171], v[212:215], v[22:25]
	v_mfma_f32_16x16x32_bf16 v[14:17], v[160:163], v[220:223], v[14:17]
	v_mfma_f32_16x16x32_bf16 v[6:9], v[168:171], v[220:223], v[6:9]
	s_setprio 0
	s_setprio 1
	v_mfma_f32_16x16x32_bf16 v[58:61], v[176:179], v[192:195], 0
	v_mfma_f32_16x16x32_bf16 v[50:53], v[184:187], v[192:195], 0
	v_mfma_f32_16x16x32_bf16 v[42:45], v[176:179], v[200:203], 0
	v_mfma_f32_16x16x32_bf16 v[34:37], v[184:187], v[200:203], 0
	v_mfma_f32_16x16x32_bf16 v[26:29], v[176:179], v[208:211], 0
	v_mfma_f32_16x16x32_bf16 v[18:21], v[184:187], v[208:211], 0
	v_mfma_f32_16x16x32_bf16 v[10:13], v[176:179], v[216:219], 0
	v_mfma_f32_16x16x32_bf16 v[2:5], v[184:187], v[216:219], 0
	v_mfma_f32_16x16x32_bf16 v[58:61], v[180:183], v[196:199], v[58:61]
	v_mfma_f32_16x16x32_bf16 v[50:53], v[188:191], v[196:199], v[50:53]
	v_mfma_f32_16x16x32_bf16 v[42:45], v[180:183], v[204:207], v[42:45]
	v_mfma_f32_16x16x32_bf16 v[34:37], v[188:191], v[204:207], v[34:37]
	v_mfma_f32_16x16x32_bf16 v[26:29], v[180:183], v[212:215], v[26:29]
	v_mfma_f32_16x16x32_bf16 v[18:21], v[188:191], v[212:215], v[18:21]
	v_mfma_f32_16x16x32_bf16 v[10:13], v[180:183], v[220:223], v[10:13]
	v_mfma_f32_16x16x32_bf16 v[2:5], v[188:191], v[220:223], v[2:5]
	s_setprio 0
	s_barrier
	s_add_i32 s83, 0, 0x18000
	v_add_u32_e32 v155, s83, v150
	s_add_i32 s84, 0, 0x1c000
	ds_read_b128 v[156:159], v155
	ds_read_b128 v[160:163], v155 offset:1024
	ds_read_b128 v[164:167], v155 offset:2048
	ds_read_b128 v[168:171], v155 offset:3072
	v_add_u32_e32 v155, s84, v150
	ds_read_b128 v[176:179], v155
	ds_read_b128 v[180:183], v155 offset:1024
	ds_read_b128 v[184:187], v155 offset:2048
	ds_read_b128 v[188:191], v155 offset:3072
	s_add_u32 s34, s34, 0x100000
	s_addc_u32 s35, s35, 0
	s_mov_b32 m0, s49
	v_lshl_add_u64 v[228:229], s[34:35], 0, v[136:137]
	ds_read_b128 v[192:195], v154 offset:32768
	ds_read_b128 v[196:199], v154 offset:33792
	ds_read_b128 v[200:203], v154 offset:34816
	ds_read_b128 v[204:207], v154 offset:35840
	ds_read_b128 v[208:211], v154 offset:36864
	ds_read_b128 v[212:215], v154 offset:37888
	ds_read_b128 v[216:219], v154 offset:38912
	ds_read_b128 v[220:223], v154 offset:39936
	global_load_lds_dwordx4 v[228:229], off
	v_lshl_add_u64 v[228:229], s[34:35], 0, v[132:133]
	s_mov_b32 m0, s50
	s_nop 0
	global_load_lds_dwordx4 v[228:229], off
	s_waitcnt vmcnt(8)
	s_waitcnt lgkmcnt(0)
	s_barrier
	s_setprio 1
	s_waitcnt lgkmcnt(0)
	v_mfma_f32_16x16x32_bf16 v[126:129], v[156:159], v[192:195], v[126:129]
	v_mfma_f32_16x16x32_bf16 v[118:121], v[164:167], v[192:195], v[118:121]
	v_mfma_f32_16x16x32_bf16 v[110:113], v[156:159], v[200:203], v[110:113]
	v_mfma_f32_16x16x32_bf16 v[102:105], v[164:167], v[200:203], v[102:105]
	v_mfma_f32_16x16x32_bf16 v[94:97], v[156:159], v[208:211], v[94:97]
	v_mfma_f32_16x16x32_bf16 v[86:89], v[164:167], v[208:211], v[86:89]
	v_mfma_f32_16x16x32_bf16 v[78:81], v[156:159], v[216:219], v[78:81]
	v_mfma_f32_16x16x32_bf16 v[70:73], v[164:167], v[216:219], v[70:73]
	v_mfma_f32_16x16x32_bf16 v[126:129], v[160:163], v[196:199], v[126:129]
	v_mfma_f32_16x16x32_bf16 v[118:121], v[168:171], v[196:199], v[118:121]
	v_mfma_f32_16x16x32_bf16 v[110:113], v[160:163], v[204:207], v[110:113]
	v_mfma_f32_16x16x32_bf16 v[102:105], v[168:171], v[204:207], v[102:105]
	v_mfma_f32_16x16x32_bf16 v[94:97], v[160:163], v[212:215], v[94:97]
	v_mfma_f32_16x16x32_bf16 v[86:89], v[168:171], v[212:215], v[86:89]
	v_mfma_f32_16x16x32_bf16 v[78:81], v[160:163], v[220:223], v[78:81]
	v_mfma_f32_16x16x32_bf16 v[70:73], v[168:171], v[220:223], v[70:73]
	s_setprio 0
	s_setprio 1
	v_mfma_f32_16x16x32_bf16 v[122:125], v[176:179], v[192:195], v[122:125]
	v_mfma_f32_16x16x32_bf16 v[114:117], v[184:187], v[192:195], v[114:117]
	v_mfma_f32_16x16x32_bf16 v[106:109], v[176:179], v[200:203], v[106:109]
	v_mfma_f32_16x16x32_bf16 v[98:101], v[184:187], v[200:203], v[98:101]
	v_mfma_f32_16x16x32_bf16 v[90:93], v[176:179], v[208:211], v[90:93]
	v_mfma_f32_16x16x32_bf16 v[82:85], v[184:187], v[208:211], v[82:85]
	v_mfma_f32_16x16x32_bf16 v[74:77], v[176:179], v[216:219], v[74:77]
	v_mfma_f32_16x16x32_bf16 v[66:69], v[184:187], v[216:219], v[66:69]
	v_mfma_f32_16x16x32_bf16 v[122:125], v[180:183], v[196:199], v[122:125]
	v_mfma_f32_16x16x32_bf16 v[114:117], v[188:191], v[196:199], v[114:117]
	v_mfma_f32_16x16x32_bf16 v[106:109], v[180:183], v[204:207], v[106:109]
	v_mfma_f32_16x16x32_bf16 v[98:101], v[188:191], v[204:207], v[98:101]
	v_mfma_f32_16x16x32_bf16 v[90:93], v[180:183], v[212:215], v[90:93]
	v_mfma_f32_16x16x32_bf16 v[82:85], v[188:191], v[212:215], v[82:85]
	v_mfma_f32_16x16x32_bf16 v[74:77], v[180:183], v[220:223], v[74:77]
	v_mfma_f32_16x16x32_bf16 v[66:69], v[188:191], v[220:223], v[66:69]
	s_setprio 0
	s_barrier
	s_add_i32 s34, s83, s3
	v_lshl_add_u64 v[146:147], v[146:147], 0, s[8:9]
	s_mov_b32 m0, s34
	ds_read_b128 v[192:195], v154 offset:49152
	ds_read_b128 v[196:199], v154 offset:50176
	ds_read_b128 v[200:203], v154 offset:51200
	ds_read_b128 v[204:207], v154 offset:52224
	ds_read_b128 v[208:211], v154 offset:53248
	ds_read_b128 v[212:215], v154 offset:54272
	ds_read_b128 v[216:219], v154 offset:55296
	ds_read_b128 v[220:223], v154 offset:56320
	global_load_lds_dwordx4 v[146:147], off
	s_add_i32 m0, s34, 0x2000
	s_add_u32 s10, s10, 0x100080
	v_lshl_add_u64 v[146:147], v[172:173], 0, s[8:9]
	s_addc_u32 s11, s11, 0
	s_add_i32 s34, s84, s3
	global_load_lds_dwordx4 v[146:147], off
	v_lshl_add_u64 v[146:147], s[10:11], 0, v[134:135]
	s_mov_b32 m0, s34
	s_nop 0
	global_load_lds_dwordx4 v[146:147], off
	v_lshl_add_u64 v[146:147], s[10:11], 0, v[130:131]
	s_add_i32 m0, s34, 0x2000
	s_nop 0
	global_load_lds_dwordx4 v[146:147], off
	v_lshl_add_u64 v[146:147], v[224:225], 0, s[8:9]
	s_mov_b32 m0, s52
	s_nop 0
	global_load_lds_dwordx4 v[146:147], off
	v_lshl_add_u64 v[146:147], v[226:227], 0, s[8:9]
	s_mov_b32 m0, s53
	s_nop 0
	global_load_lds_dwordx4 v[146:147], off
	s_waitcnt vmcnt(8)
	s_waitcnt lgkmcnt(0)
	s_barrier
	s_setprio 1
	s_waitcnt lgkmcnt(0)
	v_mfma_f32_16x16x32_bf16 v[62:65], v[156:159], v[192:195], v[62:65]
	v_mfma_f32_16x16x32_bf16 v[54:57], v[164:167], v[192:195], v[54:57]
	v_mfma_f32_16x16x32_bf16 v[46:49], v[156:159], v[200:203], v[46:49]
	v_mfma_f32_16x16x32_bf16 v[38:41], v[164:167], v[200:203], v[38:41]
	v_mfma_f32_16x16x32_bf16 v[30:33], v[156:159], v[208:211], v[30:33]
	v_mfma_f32_16x16x32_bf16 v[22:25], v[164:167], v[208:211], v[22:25]
	v_mfma_f32_16x16x32_bf16 v[14:17], v[156:159], v[216:219], v[14:17]
	v_mfma_f32_16x16x32_bf16 v[6:9], v[164:167], v[216:219], v[6:9]
	v_mfma_f32_16x16x32_bf16 v[62:65], v[160:163], v[196:199], v[62:65]
	v_mfma_f32_16x16x32_bf16 v[54:57], v[168:171], v[196:199], v[54:57]
	v_mfma_f32_16x16x32_bf16 v[46:49], v[160:163], v[204:207], v[46:49]
	v_mfma_f32_16x16x32_bf16 v[38:41], v[168:171], v[204:207], v[38:41]
	v_mfma_f32_16x16x32_bf16 v[30:33], v[160:163], v[212:215], v[30:33]
	v_mfma_f32_16x16x32_bf16 v[22:25], v[168:171], v[212:215], v[22:25]
	v_mfma_f32_16x16x32_bf16 v[14:17], v[160:163], v[220:223], v[14:17]
	v_mfma_f32_16x16x32_bf16 v[6:9], v[168:171], v[220:223], v[6:9]
	s_setprio 0
	s_setprio 1
	v_mfma_f32_16x16x32_bf16 v[58:61], v[176:179], v[192:195], v[58:61]
	v_mfma_f32_16x16x32_bf16 v[50:53], v[184:187], v[192:195], v[50:53]
	v_mfma_f32_16x16x32_bf16 v[42:45], v[176:179], v[200:203], v[42:45]
	v_mfma_f32_16x16x32_bf16 v[34:37], v[184:187], v[200:203], v[34:37]
	v_mfma_f32_16x16x32_bf16 v[26:29], v[176:179], v[208:211], v[26:29]
	v_mfma_f32_16x16x32_bf16 v[18:21], v[184:187], v[208:211], v[18:21]
	v_mfma_f32_16x16x32_bf16 v[10:13], v[176:179], v[216:219], v[10:13]
	v_mfma_f32_16x16x32_bf16 v[2:5], v[184:187], v[216:219], v[2:5]
	v_mfma_f32_16x16x32_bf16 v[58:61], v[180:183], v[196:199], v[58:61]
	v_mfma_f32_16x16x32_bf16 v[50:53], v[188:191], v[196:199], v[50:53]
	v_mfma_f32_16x16x32_bf16 v[42:45], v[180:183], v[204:207], v[42:45]
	v_mfma_f32_16x16x32_bf16 v[34:37], v[188:191], v[204:207], v[34:37]
	v_mfma_f32_16x16x32_bf16 v[26:29], v[180:183], v[212:215], v[26:29]
	v_mfma_f32_16x16x32_bf16 v[18:21], v[188:191], v[212:215], v[18:21]
	v_mfma_f32_16x16x32_bf16 v[10:13], v[180:183], v[220:223], v[10:13]
	v_mfma_f32_16x16x32_bf16 v[2:5], v[188:191], v[220:223], v[2:5]
	s_setprio 0
	s_barrier
	s_add_i32 s82, s82, 2
	s_add_u32 s46, s46, 0x100
	s_addc_u32 s47, s47, 0
	s_add_u32 s80, s80, 0x100
	s_addc_u32 s81, s81, 0
	s_cmp_gt_u32 s82, 61
	s_cbranch_scc1 .Lpeel_exit_4

.Lpeel_exit_4:
	s_and_b64 vcc, exec, s[24:25]
	s_cbranch_vccz .LBB0_783
	s_barrier

.LBB0_823:
	s_ashr_i32 s27, s26, 31
	s_lshl_b64 s[30:31], s[26:27], 21
	s_add_u32 s40, s42, s30
	s_addc_u32 s41, s43, s31
	s_and_b64 s[30:31], s[38:39], exec
	s_cselect_b32 s27, s41, s11
	s_cselect_b32 s30, s40, s10
	s_ashr_i32 s37, s36, 31
	s_lshl_b64 s[44:45], s[36:37], 21
	v_readlane_b32 s12, v255, 39
	v_readlane_b32 s13, v255, 40
	s_add_u32 s44, s12, s44
	s_addc_u32 s45, s13, s45
	s_and_b64 s[48:49], s[38:39], exec
	s_cselect_b32 s31, s45, s35
	s_cselect_b32 s37, s44, s34
	s_add_u32 s48, s10, 0x100080
	s_addc_u32 s49, s11, 0
	s_add_u32 s83, s34, 0x100
	s_addc_u32 s84, s35, 0
	s_mov_b32 s85, -2
	ds_read_b128 v[152:155], v148
	ds_read_b128 v[156:159], v148 offset:1024
	ds_read_b128 v[160:163], v148 offset:2048
	ds_read_b128 v[164:167], v148 offset:3072
	ds_read_b128 v[168:171], v149
	ds_read_b128 v[176:179], v149 offset:1024
	ds_read_b128 v[180:183], v149 offset:2048
	ds_read_b128 v[184:187], v149 offset:3072
	s_add_u32 s10, s48, 0xfff00080
	s_addc_u32 s11, s49, -1
	s_cmp_eq_u32 s85, 60
	s_cselect_b32 s35, s27, s11
	s_cselect_b32 s34, s30, s10
	s_cselect_b32 s11, s31, s84
	s_cselect_b32 s10, s37, s83
	v_lshl_add_u64 v[142:143], s[48:49], 0, v[138:139]
	s_add_i32 m0, s47, 0xc000
	ds_read_b128 v[188:191], v150
	ds_read_b128 v[192:195], v150 offset:1024
	ds_read_b128 v[196:199], v150 offset:2048
	ds_read_b128 v[200:203], v150 offset:3072
	ds_read_b128 v[204:207], v150 offset:4096
	ds_read_b128 v[208:211], v150 offset:5120
	ds_read_b128 v[212:215], v150 offset:6144
	ds_read_b128 v[216:219], v150 offset:7168
	global_load_lds_dwordx4 v[142:143], off
	v_lshl_add_u64 v[142:143], s[48:49], 0, v[140:141]
	s_add_i32 m0, s47, 0xe000
	s_nop 0
	global_load_lds_dwordx4 v[142:143], off
	s_waitcnt vmcnt(8)
	s_waitcnt lgkmcnt(0)
	s_barrier
	s_setprio 1
	s_waitcnt lgkmcnt(0)
	v_mfma_f32_16x16x32_bf16 v[126:129], v[152:155], v[188:191], 0
	v_mfma_f32_16x16x32_bf16 v[118:121], v[160:163], v[188:191], 0
	v_mfma_f32_16x16x32_bf16 v[110:113], v[152:155], v[196:199], 0
	v_mfma_f32_16x16x32_bf16 v[102:105], v[160:163], v[196:199], 0
	v_mfma_f32_16x16x32_bf16 v[94:97], v[152:155], v[204:207], 0
	v_mfma_f32_16x16x32_bf16 v[86:89], v[160:163], v[204:207], 0
	v_mfma_f32_16x16x32_bf16 v[78:81], v[152:155], v[212:215], 0
	v_mfma_f32_16x16x32_bf16 v[70:73], v[160:163], v[212:215], 0
	v_mfma_f32_16x16x32_bf16 v[126:129], v[156:159], v[192:195], v[126:129]
	v_mfma_f32_16x16x32_bf16 v[118:121], v[164:167], v[192:195], v[118:121]
	v_mfma_f32_16x16x32_bf16 v[110:113], v[156:159], v[200:203], v[110:113]
	v_mfma_f32_16x16x32_bf16 v[102:105], v[164:167], v[200:203], v[102:105]
	v_mfma_f32_16x16x32_bf16 v[94:97], v[156:159], v[208:211], v[94:97]
	v_mfma_f32_16x16x32_bf16 v[86:89], v[164:167], v[208:211], v[86:89]
	v_mfma_f32_16x16x32_bf16 v[78:81], v[156:159], v[216:219], v[78:81]
	v_mfma_f32_16x16x32_bf16 v[70:73], v[164:167], v[216:219], v[70:73]
	s_setprio 0
	s_setprio 1
	v_mfma_f32_16x16x32_bf16 v[122:125], v[168:171], v[188:191], 0
	v_mfma_f32_16x16x32_bf16 v[114:117], v[180:183], v[188:191], 0
	v_mfma_f32_16x16x32_bf16 v[106:109], v[168:171], v[196:199], 0
	v_mfma_f32_16x16x32_bf16 v[98:101], v[180:183], v[196:199], 0
	v_mfma_f32_16x16x32_bf16 v[90:93], v[168:171], v[204:207], 0
	v_mfma_f32_16x16x32_bf16 v[82:85], v[180:183], v[204:207], 0
	v_mfma_f32_16x16x32_bf16 v[74:77], v[168:171], v[212:215], 0
	v_mfma_f32_16x16x32_bf16 v[66:69], v[180:183], v[212:215], 0
	v_mfma_f32_16x16x32_bf16 v[122:125], v[176:179], v[192:195], v[122:125]
	v_mfma_f32_16x16x32_bf16 v[114:117], v[184:187], v[192:195], v[114:117]
	v_mfma_f32_16x16x32_bf16 v[106:109], v[176:179], v[200:203], v[106:109]
	v_mfma_f32_16x16x32_bf16 v[98:101], v[184:187], v[200:203], v[98:101]
	v_mfma_f32_16x16x32_bf16 v[90:93], v[176:179], v[208:211], v[90:93]
	v_mfma_f32_16x16x32_bf16 v[82:85], v[184:187], v[208:211], v[82:85]
	v_mfma_f32_16x16x32_bf16 v[74:77], v[176:179], v[216:219], v[74:77]
	v_mfma_f32_16x16x32_bf16 v[66:69], v[184:187], v[216:219], v[66:69]
	s_setprio 0
	s_barrier
	s_add_i32 s86, s61, s51
	v_lshl_add_u64 v[142:143], s[10:11], 0, v[132:133]
	s_mov_b32 m0, s86
	ds_read_b128 v[188:191], v150 offset:16384
	ds_read_b128 v[192:195], v150 offset:17408
	ds_read_b128 v[196:199], v150 offset:18432
	ds_read_b128 v[200:203], v150 offset:19456
	ds_read_b128 v[204:207], v150 offset:20480
	ds_read_b128 v[208:211], v150 offset:21504
	ds_read_b128 v[212:215], v150 offset:22528
	ds_read_b128 v[216:219], v150 offset:23552
	global_load_lds_dwordx4 v[142:143], off
	s_add_i32 m0, s86, 0x2000
	s_add_u32 s86, s10, 0x100000
	v_lshl_add_u64 v[172:173], s[10:11], 0, v[136:137]
	s_addc_u32 s87, s11, 0
	s_add_i32 s88, s62, s51
	global_load_lds_dwordx4 v[172:173], off
	v_lshl_add_u64 v[220:221], s[86:87], 0, v[132:133]
	s_mov_b32 m0, s88
	v_lshl_add_u64 v[222:223], s[34:35], 0, v[134:135]
	global_load_lds_dwordx4 v[220:221], off
	v_lshl_add_u64 v[220:221], s[86:87], 0, v[136:137]
	s_add_i32 m0, s88, 0x2000
	s_nop 0
	global_load_lds_dwordx4 v[220:221], off
	v_lshl_add_u64 v[220:221], s[34:35], 0, v[130:131]
	s_mov_b32 m0, s47
	s_nop 0
	global_load_lds_dwordx4 v[220:221], off
	s_mov_b32 m0, s54
	s_nop 0
	global_load_lds_dwordx4 v[222:223], off
	s_waitcnt vmcnt(8)
	s_waitcnt lgkmcnt(0)
	s_barrier
	s_setprio 1
	s_waitcnt lgkmcnt(0)
	v_mfma_f32_16x16x32_bf16 v[62:65], v[152:155], v[188:191], 0
	v_mfma_f32_16x16x32_bf16 v[54:57], v[160:163], v[188:191], 0
	v_mfma_f32_16x16x32_bf16 v[46:49], v[152:155], v[196:199], 0
	v_mfma_f32_16x16x32_bf16 v[38:41], v[160:163], v[196:199], 0
	v_mfma_f32_16x16x32_bf16 v[30:33], v[152:155], v[204:207], 0
	v_mfma_f32_16x16x32_bf16 v[22:25], v[160:163], v[204:207], 0
	v_mfma_f32_16x16x32_bf16 v[14:17], v[152:155], v[212:215], 0
	v_mfma_f32_16x16x32_bf16 v[6:9], v[160:163], v[212:215], 0
	v_mfma_f32_16x16x32_bf16 v[62:65], v[156:159], v[192:195], v[62:65]
	v_mfma_f32_16x16x32_bf16 v[54:57], v[164:167], v[192:195], v[54:57]
	v_mfma_f32_16x16x32_bf16 v[46:49], v[156:159], v[200:203], v[46:49]
	v_mfma_f32_16x16x32_bf16 v[38:41], v[164:167], v[200:203], v[38:41]
	v_mfma_f32_16x16x32_bf16 v[30:33], v[156:159], v[208:211], v[30:33]
	v_mfma_f32_16x16x32_bf16 v[22:25], v[164:167], v[208:211], v[22:25]
	v_mfma_f32_16x16x32_bf16 v[14:17], v[156:159], v[216:219], v[14:17]
	v_mfma_f32_16x16x32_bf16 v[6:9], v[164:167], v[216:219], v[6:9]
	s_setprio 0
	s_setprio 1
	v_mfma_f32_16x16x32_bf16 v[58:61], v[168:171], v[188:191], 0
	v_mfma_f32_16x16x32_bf16 v[50:53], v[180:183], v[188:191], 0
	v_mfma_f32_16x16x32_bf16 v[42:45], v[168:171], v[196:199], 0
	v_mfma_f32_16x16x32_bf16 v[34:37], v[180:183], v[196:199], 0
	v_mfma_f32_16x16x32_bf16 v[26:29], v[168:171], v[204:207], 0
	v_mfma_f32_16x16x32_bf16 v[18:21], v[180:183], v[204:207], 0
	v_mfma_f32_16x16x32_bf16 v[10:13], v[168:171], v[212:215], 0
	v_mfma_f32_16x16x32_bf16 v[2:5], v[180:183], v[212:215], 0
	v_mfma_f32_16x16x32_bf16 v[58:61], v[176:179], v[192:195], v[58:61]
	v_mfma_f32_16x16x32_bf16 v[50:53], v[184:187], v[192:195], v[50:53]
	v_mfma_f32_16x16x32_bf16 v[42:45], v[176:179], v[200:203], v[42:45]
	v_mfma_f32_16x16x32_bf16 v[34:37], v[184:187], v[200:203], v[34:37]
	v_mfma_f32_16x16x32_bf16 v[26:29], v[176:179], v[208:211], v[26:29]
	v_mfma_f32_16x16x32_bf16 v[18:21], v[184:187], v[208:211], v[18:21]
	v_mfma_f32_16x16x32_bf16 v[10:13], v[176:179], v[216:219], v[10:13]
	v_mfma_f32_16x16x32_bf16 v[2:5], v[184:187], v[216:219], v[2:5]
	s_setprio 0
	s_barrier
	s_add_i32 s86, 0, 0x18000
	v_add_u32_e32 v151, s86, v146
	s_add_i32 s87, 0, 0x1c000
	ds_read_b128 v[152:155], v151
	ds_read_b128 v[156:159], v151 offset:1024
	ds_read_b128 v[160:163], v151 offset:2048
	ds_read_b128 v[164:167], v151 offset:3072
	v_add_u32_e32 v151, s87, v146
	ds_read_b128 v[168:171], v151
	ds_read_b128 v[176:179], v151 offset:1024
	ds_read_b128 v[180:183], v151 offset:2048
	ds_read_b128 v[184:187], v151 offset:3072
	s_add_u32 s34, s34, 0x100000
	s_addc_u32 s35, s35, 0
	s_mov_b32 m0, s55
	v_lshl_add_u64 v[224:225], s[34:35], 0, v[130:131]
	ds_read_b128 v[188:191], v150 offset:32768
	ds_read_b128 v[192:195], v150 offset:33792
	ds_read_b128 v[196:199], v150 offset:34816
	ds_read_b128 v[200:203], v150 offset:35840
	ds_read_b128 v[204:207], v150 offset:36864
	ds_read_b128 v[208:211], v150 offset:37888
	ds_read_b128 v[212:215], v150 offset:38912
	ds_read_b128 v[216:219], v150 offset:39936
	global_load_lds_dwordx4 v[224:225], off
	v_lshl_add_u64 v[224:225], s[34:35], 0, v[134:135]
	s_mov_b32 m0, s56
	s_nop 0
	global_load_lds_dwordx4 v[224:225], off
	s_waitcnt vmcnt(8)
	s_waitcnt lgkmcnt(0)
	s_barrier
	s_setprio 1
	s_waitcnt lgkmcnt(0)
	v_mfma_f32_16x16x32_bf16 v[126:129], v[152:155], v[188:191], v[126:129]
	v_mfma_f32_16x16x32_bf16 v[118:121], v[160:163], v[188:191], v[118:121]
	v_mfma_f32_16x16x32_bf16 v[110:113], v[152:155], v[196:199], v[110:113]
	v_mfma_f32_16x16x32_bf16 v[102:105], v[160:163], v[196:199], v[102:105]
	v_mfma_f32_16x16x32_bf16 v[94:97], v[152:155], v[204:207], v[94:97]
	v_mfma_f32_16x16x32_bf16 v[86:89], v[160:163], v[204:207], v[86:89]
	v_mfma_f32_16x16x32_bf16 v[78:81], v[152:155], v[212:215], v[78:81]
	v_mfma_f32_16x16x32_bf16 v[70:73], v[160:163], v[212:215], v[70:73]
	v_mfma_f32_16x16x32_bf16 v[126:129], v[156:159], v[192:195], v[126:129]
	v_mfma_f32_16x16x32_bf16 v[118:121], v[164:167], v[192:195], v[118:121]
	v_mfma_f32_16x16x32_bf16 v[110:113], v[156:159], v[200:203], v[110:113]
	v_mfma_f32_16x16x32_bf16 v[102:105], v[164:167], v[200:203], v[102:105]
	v_mfma_f32_16x16x32_bf16 v[94:97], v[156:159], v[208:211], v[94:97]
	v_mfma_f32_16x16x32_bf16 v[86:89], v[164:167], v[208:211], v[86:89]
	v_mfma_f32_16x16x32_bf16 v[78:81], v[156:159], v[216:219], v[78:81]
	v_mfma_f32_16x16x32_bf16 v[70:73], v[164:167], v[216:219], v[70:73]
	s_setprio 0
	s_setprio 1
	v_mfma_f32_16x16x32_bf16 v[122:125], v[168:171], v[188:191], v[122:125]
	v_mfma_f32_16x16x32_bf16 v[114:117], v[180:183], v[188:191], v[114:117]
	v_mfma_f32_16x16x32_bf16 v[106:109], v[168:171], v[196:199], v[106:109]
	v_mfma_f32_16x16x32_bf16 v[98:101], v[180:183], v[196:199], v[98:101]
	v_mfma_f32_16x16x32_bf16 v[90:93], v[168:171], v[204:207], v[90:93]
	v_mfma_f32_16x16x32_bf16 v[82:85], v[180:183], v[204:207], v[82:85]
	v_mfma_f32_16x16x32_bf16 v[74:77], v[168:171], v[212:215], v[74:77]
	v_mfma_f32_16x16x32_bf16 v[66:69], v[180:183], v[212:215], v[66:69]
	v_mfma_f32_16x16x32_bf16 v[122:125], v[176:179], v[192:195], v[122:125]
	v_mfma_f32_16x16x32_bf16 v[114:117], v[184:187], v[192:195], v[114:117]
	v_mfma_f32_16x16x32_bf16 v[106:109], v[176:179], v[200:203], v[106:109]
	v_mfma_f32_16x16x32_bf16 v[98:101], v[184:187], v[200:203], v[98:101]
	v_mfma_f32_16x16x32_bf16 v[90:93], v[176:179], v[208:211], v[90:93]
	v_mfma_f32_16x16x32_bf16 v[82:85], v[184:187], v[208:211], v[82:85]
	v_mfma_f32_16x16x32_bf16 v[74:77], v[176:179], v[216:219], v[74:77]
	v_mfma_f32_16x16x32_bf16 v[66:69], v[184:187], v[216:219], v[66:69]
	s_setprio 0
	s_barrier
	s_add_i32 s34, s86, s51
	v_lshl_add_u64 v[142:143], v[142:143], 0, s[8:9]
	s_mov_b32 m0, s34
	ds_read_b128 v[188:191], v150 offset:49152
	ds_read_b128 v[192:195], v150 offset:50176
	ds_read_b128 v[196:199], v150 offset:51200
	ds_read_b128 v[200:203], v150 offset:52224
	ds_read_b128 v[204:207], v150 offset:53248
	ds_read_b128 v[208:211], v150 offset:54272
	ds_read_b128 v[212:215], v150 offset:55296
	ds_read_b128 v[216:219], v150 offset:56320
	global_load_lds_dwordx4 v[142:143], off
	s_add_i32 m0, s34, 0x2000
	s_add_u32 s10, s10, 0x100080
	v_lshl_add_u64 v[142:143], v[172:173], 0, s[8:9]
	s_addc_u32 s11, s11, 0
	s_add_i32 s34, s87, s51
	global_load_lds_dwordx4 v[142:143], off
	v_lshl_add_u64 v[142:143], s[10:11], 0, v[132:133]
	s_mov_b32 m0, s34
	s_nop 0
	global_load_lds_dwordx4 v[142:143], off
	v_lshl_add_u64 v[142:143], s[10:11], 0, v[136:137]
	s_add_i32 m0, s34, 0x2000
	s_nop 0
	global_load_lds_dwordx4 v[142:143], off
	v_lshl_add_u64 v[142:143], v[220:221], 0, s[8:9]
	s_mov_b32 m0, s57
	s_nop 0
	global_load_lds_dwordx4 v[142:143], off
	v_lshl_add_u64 v[142:143], v[222:223], 0, s[8:9]
	s_mov_b32 m0, s58
	s_nop 0
	global_load_lds_dwordx4 v[142:143], off
	s_waitcnt vmcnt(8)
	s_waitcnt lgkmcnt(0)
	s_barrier
	s_setprio 1
	s_waitcnt lgkmcnt(0)
	v_mfma_f32_16x16x32_bf16 v[62:65], v[152:155], v[188:191], v[62:65]
	v_mfma_f32_16x16x32_bf16 v[54:57], v[160:163], v[188:191], v[54:57]
	v_mfma_f32_16x16x32_bf16 v[46:49], v[152:155], v[196:199], v[46:49]
	v_mfma_f32_16x16x32_bf16 v[38:41], v[160:163], v[196:199], v[38:41]
	v_mfma_f32_16x16x32_bf16 v[30:33], v[152:155], v[204:207], v[30:33]
	v_mfma_f32_16x16x32_bf16 v[22:25], v[160:163], v[204:207], v[22:25]
	v_mfma_f32_16x16x32_bf16 v[14:17], v[152:155], v[212:215], v[14:17]
	v_mfma_f32_16x16x32_bf16 v[6:9], v[160:163], v[212:215], v[6:9]
	v_mfma_f32_16x16x32_bf16 v[62:65], v[156:159], v[192:195], v[62:65]
	v_mfma_f32_16x16x32_bf16 v[54:57], v[164:167], v[192:195], v[54:57]
	v_mfma_f32_16x16x32_bf16 v[46:49], v[156:159], v[200:203], v[46:49]
	v_mfma_f32_16x16x32_bf16 v[38:41], v[164:167], v[200:203], v[38:41]
	v_mfma_f32_16x16x32_bf16 v[30:33], v[156:159], v[208:211], v[30:33]
	v_mfma_f32_16x16x32_bf16 v[22:25], v[164:167], v[208:211], v[22:25]
	v_mfma_f32_16x16x32_bf16 v[14:17], v[156:159], v[216:219], v[14:17]
	v_mfma_f32_16x16x32_bf16 v[6:9], v[164:167], v[216:219], v[6:9]
	s_setprio 0
	s_setprio 1
	v_mfma_f32_16x16x32_bf16 v[58:61], v[168:171], v[188:191], v[58:61]
	v_mfma_f32_16x16x32_bf16 v[50:53], v[180:183], v[188:191], v[50:53]
	v_mfma_f32_16x16x32_bf16 v[42:45], v[168:171], v[196:199], v[42:45]
	v_mfma_f32_16x16x32_bf16 v[34:37], v[180:183], v[196:199], v[34:37]
	v_mfma_f32_16x16x32_bf16 v[26:29], v[168:171], v[204:207], v[26:29]
	v_mfma_f32_16x16x32_bf16 v[18:21], v[180:183], v[204:207], v[18:21]
	v_mfma_f32_16x16x32_bf16 v[10:13], v[168:171], v[212:215], v[10:13]
	v_mfma_f32_16x16x32_bf16 v[2:5], v[180:183], v[212:215], v[2:5]
	v_mfma_f32_16x16x32_bf16 v[58:61], v[176:179], v[192:195], v[58:61]
	v_mfma_f32_16x16x32_bf16 v[50:53], v[184:187], v[192:195], v[50:53]
	v_mfma_f32_16x16x32_bf16 v[42:45], v[176:179], v[200:203], v[42:45]
	v_mfma_f32_16x16x32_bf16 v[34:37], v[184:187], v[200:203], v[34:37]
	v_mfma_f32_16x16x32_bf16 v[26:29], v[176:179], v[208:211], v[26:29]
	v_mfma_f32_16x16x32_bf16 v[18:21], v[184:187], v[208:211], v[18:21]
	v_mfma_f32_16x16x32_bf16 v[10:13], v[176:179], v[216:219], v[10:13]
	v_mfma_f32_16x16x32_bf16 v[2:5], v[184:187], v[216:219], v[2:5]
	s_setprio 0
	s_barrier
	s_add_i32 s85, s85, 2
	s_add_u32 s48, s48, 0x100
	s_addc_u32 s49, s49, 0
	s_add_u32 s83, s83, 0x100
	s_addc_u32 s84, s84, 0
	s_cmp_gt_u32 s85, 61
	s_cbranch_scc1 .Lpeel_exit_5

.LBB0_922:
	s_add_u32 s42, s42, 0x2b0080
	s_addc_u32 s43, s43, 0
	s_add_u32 s62, s34, 0x100
	s_addc_u32 s63, s35, 0
	s_mov_b32 s64, -2
	ds_read_b128 v[152:155], v149
	ds_read_b128 v[156:159], v149 offset:1024
	ds_read_b128 v[160:163], v149 offset:2048
	ds_read_b128 v[164:167], v149 offset:3072
	ds_read_b128 v[168:171], v150
	ds_read_b128 v[176:179], v150 offset:1024
	ds_read_b128 v[180:183], v150 offset:2048
	ds_read_b128 v[184:187], v150 offset:3072
	s_add_u32 s10, s42, 0xffd50080
	s_addc_u32 s11, s43, -1
	s_cmpk_eq_i32 s64, 0xa8
	s_cselect_b32 s35, s7, s11
	s_cselect_b32 s34, s6, s10
	s_cselect_b32 s11, s41, s63
	s_cselect_b32 s10, s40, s62
	v_lshl_add_u64 v[144:145], s[42:43], 0, v[136:137]
	s_add_i32 m0, s44, 0xc000
	ds_read_b128 v[188:191], v151
	ds_read_b128 v[192:195], v151 offset:1024
	ds_read_b128 v[196:199], v151 offset:2048
	ds_read_b128 v[200:203], v151 offset:3072
	ds_read_b128 v[204:207], v151 offset:4096
	ds_read_b128 v[208:211], v151 offset:5120
	ds_read_b128 v[212:215], v151 offset:6144
	ds_read_b128 v[216:219], v151 offset:7168
	global_load_lds_dwordx4 v[144:145], off
	v_lshl_add_u64 v[144:145], s[42:43], 0, v[138:139]
	s_add_i32 m0, s44, 0xe000
	s_nop 0
	global_load_lds_dwordx4 v[144:145], off
	s_waitcnt vmcnt(8)
	s_waitcnt lgkmcnt(0)
	s_barrier
	s_setprio 1
	s_waitcnt lgkmcnt(0)
	v_mfma_f32_16x16x32_bf16 v[124:127], v[152:155], v[188:191], 0
	v_mfma_f32_16x16x32_bf16 v[120:123], v[160:163], v[188:191], 0
	v_mfma_f32_16x16x32_bf16 v[112:115], v[152:155], v[196:199], 0
	v_mfma_f32_16x16x32_bf16 v[104:107], v[160:163], v[196:199], 0
	v_mfma_f32_16x16x32_bf16 v[96:99], v[152:155], v[204:207], 0
	v_mfma_f32_16x16x32_bf16 v[88:91], v[160:163], v[204:207], 0
	v_mfma_f32_16x16x32_bf16 v[80:83], v[152:155], v[212:215], 0
	v_mfma_f32_16x16x32_bf16 v[72:75], v[160:163], v[212:215], 0
	v_mfma_f32_16x16x32_bf16 v[124:127], v[156:159], v[192:195], v[124:127]
	v_mfma_f32_16x16x32_bf16 v[120:123], v[164:167], v[192:195], v[120:123]
	v_mfma_f32_16x16x32_bf16 v[112:115], v[156:159], v[200:203], v[112:115]
	v_mfma_f32_16x16x32_bf16 v[104:107], v[164:167], v[200:203], v[104:107]
	v_mfma_f32_16x16x32_bf16 v[96:99], v[156:159], v[208:211], v[96:99]
	v_mfma_f32_16x16x32_bf16 v[88:91], v[164:167], v[208:211], v[88:91]
	v_mfma_f32_16x16x32_bf16 v[80:83], v[156:159], v[216:219], v[80:83]
	v_mfma_f32_16x16x32_bf16 v[72:75], v[164:167], v[216:219], v[72:75]
	s_setprio 0
	s_setprio 1
	v_mfma_f32_16x16x32_bf16 v[116:119], v[168:171], v[188:191], 0
	v_mfma_f32_16x16x32_bf16 v[108:111], v[180:183], v[188:191], 0
	v_mfma_f32_16x16x32_bf16 v[100:103], v[168:171], v[196:199], 0
	v_mfma_f32_16x16x32_bf16 v[92:95], v[180:183], v[196:199], 0
	v_mfma_f32_16x16x32_bf16 v[84:87], v[168:171], v[204:207], 0
	v_mfma_f32_16x16x32_bf16 v[76:79], v[180:183], v[204:207], 0
	v_mfma_f32_16x16x32_bf16 v[68:71], v[168:171], v[212:215], 0
	v_mfma_f32_16x16x32_bf16 v[64:67], v[180:183], v[212:215], 0
	v_mfma_f32_16x16x32_bf16 v[116:119], v[176:179], v[192:195], v[116:119]
	v_mfma_f32_16x16x32_bf16 v[108:111], v[184:187], v[192:195], v[108:111]
	v_mfma_f32_16x16x32_bf16 v[100:103], v[176:179], v[200:203], v[100:103]
	v_mfma_f32_16x16x32_bf16 v[92:95], v[184:187], v[200:203], v[92:95]
	v_mfma_f32_16x16x32_bf16 v[84:87], v[176:179], v[208:211], v[84:87]
	v_mfma_f32_16x16x32_bf16 v[76:79], v[184:187], v[208:211], v[76:79]
	v_mfma_f32_16x16x32_bf16 v[68:71], v[176:179], v[216:219], v[68:71]
	v_mfma_f32_16x16x32_bf16 v[64:67], v[184:187], v[216:219], v[64:67]
	s_setprio 0
	s_barrier
	s_add_i32 s65, s52, s3
	v_lshl_add_u64 v[144:145], s[10:11], 0, v[132:133]
	s_mov_b32 m0, s65
	ds_read_b128 v[188:191], v151 offset:16384
	ds_read_b128 v[192:195], v151 offset:17408
	ds_read_b128 v[196:199], v151 offset:18432
	ds_read_b128 v[200:203], v151 offset:19456
	ds_read_b128 v[204:207], v151 offset:20480
	ds_read_b128 v[208:211], v151 offset:21504
	ds_read_b128 v[212:215], v151 offset:22528
	ds_read_b128 v[216:219], v151 offset:23552
	global_load_lds_dwordx4 v[144:145], off
	s_add_i32 m0, s65, 0x2000
	s_add_u32 s66, s10, 0x2b0000
	v_lshl_add_u64 v[172:173], s[10:11], 0, v[128:129]
	s_addc_u32 s67, s11, 0
	s_add_i32 s65, s53, s3
	global_load_lds_dwordx4 v[172:173], off
	v_lshl_add_u64 v[220:221], s[66:67], 0, v[132:133]
	s_mov_b32 m0, s65
	v_lshl_add_u64 v[222:223], s[34:35], 0, v[130:131]
	global_load_lds_dwordx4 v[220:221], off
	v_lshl_add_u64 v[220:221], s[66:67], 0, v[128:129]
	s_add_i32 m0, s65, 0x2000
	s_nop 0
	global_load_lds_dwordx4 v[220:221], off
	v_lshl_add_u64 v[220:221], s[34:35], 0, v[134:135]
	s_mov_b32 m0, s44
	s_nop 0
	global_load_lds_dwordx4 v[220:221], off
	s_mov_b32 m0, s45
	s_nop 0
	global_load_lds_dwordx4 v[222:223], off
	s_waitcnt vmcnt(8)
	s_waitcnt lgkmcnt(0)
	s_barrier
	s_setprio 1
	s_waitcnt lgkmcnt(0)
	v_mfma_f32_16x16x32_bf16 v[60:63], v[152:155], v[188:191], 0
	v_mfma_f32_16x16x32_bf16 v[56:59], v[160:163], v[188:191], 0
	v_mfma_f32_16x16x32_bf16 v[48:51], v[152:155], v[196:199], 0
	v_mfma_f32_16x16x32_bf16 v[40:43], v[160:163], v[196:199], 0
	v_mfma_f32_16x16x32_bf16 v[32:35], v[152:155], v[204:207], 0
	v_mfma_f32_16x16x32_bf16 v[24:27], v[160:163], v[204:207], 0
	v_mfma_f32_16x16x32_bf16 v[16:19], v[152:155], v[212:215], 0
	v_mfma_f32_16x16x32_bf16 v[8:11], v[160:163], v[212:215], 0
	v_mfma_f32_16x16x32_bf16 v[60:63], v[156:159], v[192:195], v[60:63]
	v_mfma_f32_16x16x32_bf16 v[56:59], v[164:167], v[192:195], v[56:59]
	v_mfma_f32_16x16x32_bf16 v[48:51], v[156:159], v[200:203], v[48:51]
	v_mfma_f32_16x16x32_bf16 v[40:43], v[164:167], v[200:203], v[40:43]
	v_mfma_f32_16x16x32_bf16 v[32:35], v[156:159], v[208:211], v[32:35]
	v_mfma_f32_16x16x32_bf16 v[24:27], v[164:167], v[208:211], v[24:27]
	v_mfma_f32_16x16x32_bf16 v[16:19], v[156:159], v[216:219], v[16:19]
	v_mfma_f32_16x16x32_bf16 v[8:11], v[164:167], v[216:219], v[8:11]
	s_setprio 0
	s_setprio 1
	v_mfma_f32_16x16x32_bf16 v[52:55], v[168:171], v[188:191], 0
	v_mfma_f32_16x16x32_bf16 v[44:47], v[180:183], v[188:191], 0
	v_mfma_f32_16x16x32_bf16 v[36:39], v[168:171], v[196:199], 0
	v_mfma_f32_16x16x32_bf16 v[28:31], v[180:183], v[196:199], 0
	v_mfma_f32_16x16x32_bf16 v[20:23], v[168:171], v[204:207], 0
	v_mfma_f32_16x16x32_bf16 v[12:15], v[180:183], v[204:207], 0
	v_mfma_f32_16x16x32_bf16 v[4:7], v[168:171], v[212:215], 0
	v_mfma_f32_16x16x32_bf16 v[0:3], v[180:183], v[212:215], 0
	v_mfma_f32_16x16x32_bf16 v[52:55], v[176:179], v[192:195], v[52:55]
	v_mfma_f32_16x16x32_bf16 v[44:47], v[184:187], v[192:195], v[44:47]
	v_mfma_f32_16x16x32_bf16 v[36:39], v[176:179], v[200:203], v[36:39]
	v_mfma_f32_16x16x32_bf16 v[28:31], v[184:187], v[200:203], v[28:31]
	v_mfma_f32_16x16x32_bf16 v[20:23], v[176:179], v[208:211], v[20:23]
	v_mfma_f32_16x16x32_bf16 v[12:15], v[184:187], v[208:211], v[12:15]
	v_mfma_f32_16x16x32_bf16 v[4:7], v[176:179], v[216:219], v[4:7]
	v_mfma_f32_16x16x32_bf16 v[0:3], v[184:187], v[216:219], v[0:3]
	s_setprio 0
	s_barrier
	s_add_i32 s65, 0, 0x18000
	s_add_i32 s66, 0, 0x1c000
	v_add_u32_e32 v164, s65, v147
	v_add_u32_e32 v175, s66, v147
	ds_read_b128 v[152:155], v164
	ds_read_b128 v[156:159], v164 offset:1024
	ds_read_b128 v[160:163], v164 offset:2048
	ds_read_b128 v[164:167], v164 offset:3072
	ds_read_b128 v[168:171], v175
	ds_read_b128 v[176:179], v175 offset:1024
	ds_read_b128 v[180:183], v175 offset:2048
	ds_read_b128 v[184:187], v175 offset:3072
	s_add_u32 s34, s34, 0x2b0000
	s_addc_u32 s35, s35, 0
	s_mov_b32 m0, s46
	v_lshl_add_u64 v[224:225], s[34:35], 0, v[134:135]
	ds_read_b128 v[188:191], v151 offset:32768
	ds_read_b128 v[192:195], v151 offset:33792
	ds_read_b128 v[196:199], v151 offset:34816
	ds_read_b128 v[200:203], v151 offset:35840
	ds_read_b128 v[204:207], v151 offset:36864
	ds_read_b128 v[208:211], v151 offset:37888
	ds_read_b128 v[212:215], v151 offset:38912
	ds_read_b128 v[216:219], v151 offset:39936
	global_load_lds_dwordx4 v[224:225], off
	v_lshl_add_u64 v[224:225], s[34:35], 0, v[130:131]
	s_mov_b32 m0, s47
	s_nop 0
	global_load_lds_dwordx4 v[224:225], off
	s_waitcnt vmcnt(8)
	s_waitcnt lgkmcnt(0)
	s_barrier
	s_setprio 1
	s_waitcnt lgkmcnt(0)
	v_mfma_f32_16x16x32_bf16 v[124:127], v[152:155], v[188:191], v[124:127]
	v_mfma_f32_16x16x32_bf16 v[120:123], v[160:163], v[188:191], v[120:123]
	v_mfma_f32_16x16x32_bf16 v[112:115], v[152:155], v[196:199], v[112:115]
	v_mfma_f32_16x16x32_bf16 v[104:107], v[160:163], v[196:199], v[104:107]
	v_mfma_f32_16x16x32_bf16 v[96:99], v[152:155], v[204:207], v[96:99]
	v_mfma_f32_16x16x32_bf16 v[88:91], v[160:163], v[204:207], v[88:91]
	v_mfma_f32_16x16x32_bf16 v[80:83], v[152:155], v[212:215], v[80:83]
	v_mfma_f32_16x16x32_bf16 v[72:75], v[160:163], v[212:215], v[72:75]
	v_mfma_f32_16x16x32_bf16 v[124:127], v[156:159], v[192:195], v[124:127]
	v_mfma_f32_16x16x32_bf16 v[120:123], v[164:167], v[192:195], v[120:123]
	v_mfma_f32_16x16x32_bf16 v[112:115], v[156:159], v[200:203], v[112:115]
	v_mfma_f32_16x16x32_bf16 v[104:107], v[164:167], v[200:203], v[104:107]
	v_mfma_f32_16x16x32_bf16 v[96:99], v[156:159], v[208:211], v[96:99]
	v_mfma_f32_16x16x32_bf16 v[88:91], v[164:167], v[208:211], v[88:91]
	v_mfma_f32_16x16x32_bf16 v[80:83], v[156:159], v[216:219], v[80:83]
	v_mfma_f32_16x16x32_bf16 v[72:75], v[164:167], v[216:219], v[72:75]
	s_setprio 0
	s_setprio 1
	v_mfma_f32_16x16x32_bf16 v[116:119], v[168:171], v[188:191], v[116:119]
	v_mfma_f32_16x16x32_bf16 v[108:111], v[180:183], v[188:191], v[108:111]
	v_mfma_f32_16x16x32_bf16 v[100:103], v[168:171], v[196:199], v[100:103]
	v_mfma_f32_16x16x32_bf16 v[92:95], v[180:183], v[196:199], v[92:95]
	v_mfma_f32_16x16x32_bf16 v[84:87], v[168:171], v[204:207], v[84:87]
	v_mfma_f32_16x16x32_bf16 v[76:79], v[180:183], v[204:207], v[76:79]
	v_mfma_f32_16x16x32_bf16 v[68:71], v[168:171], v[212:215], v[68:71]
	v_mfma_f32_16x16x32_bf16 v[64:67], v[180:183], v[212:215], v[64:67]
	v_mfma_f32_16x16x32_bf16 v[116:119], v[176:179], v[192:195], v[116:119]
	v_mfma_f32_16x16x32_bf16 v[108:111], v[184:187], v[192:195], v[108:111]
	v_mfma_f32_16x16x32_bf16 v[100:103], v[176:179], v[200:203], v[100:103]
	v_mfma_f32_16x16x32_bf16 v[92:95], v[184:187], v[200:203], v[92:95]
	v_mfma_f32_16x16x32_bf16 v[84:87], v[176:179], v[208:211], v[84:87]
	v_mfma_f32_16x16x32_bf16 v[76:79], v[184:187], v[208:211], v[76:79]
	v_mfma_f32_16x16x32_bf16 v[68:71], v[176:179], v[216:219], v[68:71]
	v_mfma_f32_16x16x32_bf16 v[64:67], v[184:187], v[216:219], v[64:67]
	s_setprio 0
	s_barrier
	s_add_i32 s34, s65, s3
	v_lshl_add_u64 v[144:145], v[144:145], 0, s[14:15]
	s_mov_b32 m0, s34
	ds_read_b128 v[188:191], v151 offset:49152
	ds_read_b128 v[192:195], v151 offset:50176
	ds_read_b128 v[196:199], v151 offset:51200
	ds_read_b128 v[200:203], v151 offset:52224
	ds_read_b128 v[204:207], v151 offset:53248
	ds_read_b128 v[208:211], v151 offset:54272
	ds_read_b128 v[212:215], v151 offset:55296
	ds_read_b128 v[216:219], v151 offset:56320
	global_load_lds_dwordx4 v[144:145], off
	s_add_i32 m0, s34, 0x2000
	s_add_u32 s10, s10, 0x2b0080
	v_lshl_add_u64 v[144:145], v[172:173], 0, s[14:15]
	s_addc_u32 s11, s11, 0
	s_add_i32 s34, s66, s3
	global_load_lds_dwordx4 v[144:145], off
	v_lshl_add_u64 v[144:145], s[10:11], 0, v[132:133]
	s_mov_b32 m0, s34
	s_nop 0
	global_load_lds_dwordx4 v[144:145], off
	v_lshl_add_u64 v[144:145], s[10:11], 0, v[128:129]
	s_add_i32 m0, s34, 0x2000
	s_nop 0
	global_load_lds_dwordx4 v[144:145], off
	v_lshl_add_u64 v[144:145], v[220:221], 0, s[14:15]
	s_mov_b32 m0, s49
	s_nop 0
	global_load_lds_dwordx4 v[144:145], off
	v_lshl_add_u64 v[144:145], v[222:223], 0, s[14:15]
	s_mov_b32 m0, s50
	s_nop 0
	global_load_lds_dwordx4 v[144:145], off
	s_waitcnt vmcnt(8)
	s_waitcnt lgkmcnt(0)
	s_barrier
	s_setprio 1
	s_waitcnt lgkmcnt(0)
	v_mfma_f32_16x16x32_bf16 v[60:63], v[152:155], v[188:191], v[60:63]
	v_mfma_f32_16x16x32_bf16 v[56:59], v[160:163], v[188:191], v[56:59]
	v_mfma_f32_16x16x32_bf16 v[48:51], v[152:155], v[196:199], v[48:51]
	v_mfma_f32_16x16x32_bf16 v[40:43], v[160:163], v[196:199], v[40:43]
	v_mfma_f32_16x16x32_bf16 v[32:35], v[152:155], v[204:207], v[32:35]
	v_mfma_f32_16x16x32_bf16 v[24:27], v[160:163], v[204:207], v[24:27]
	v_mfma_f32_16x16x32_bf16 v[16:19], v[152:155], v[212:215], v[16:19]
	v_mfma_f32_16x16x32_bf16 v[8:11], v[160:163], v[212:215], v[8:11]
	v_mfma_f32_16x16x32_bf16 v[60:63], v[156:159], v[192:195], v[60:63]
	v_mfma_f32_16x16x32_bf16 v[56:59], v[164:167], v[192:195], v[56:59]
	v_mfma_f32_16x16x32_bf16 v[48:51], v[156:159], v[200:203], v[48:51]
	v_mfma_f32_16x16x32_bf16 v[40:43], v[164:167], v[200:203], v[40:43]
	v_mfma_f32_16x16x32_bf16 v[32:35], v[156:159], v[208:211], v[32:35]
	v_mfma_f32_16x16x32_bf16 v[24:27], v[164:167], v[208:211], v[24:27]
	v_mfma_f32_16x16x32_bf16 v[16:19], v[156:159], v[216:219], v[16:19]
	v_mfma_f32_16x16x32_bf16 v[8:11], v[164:167], v[216:219], v[8:11]
	s_setprio 0
	s_setprio 1
	v_mfma_f32_16x16x32_bf16 v[52:55], v[168:171], v[188:191], v[52:55]
	v_mfma_f32_16x16x32_bf16 v[44:47], v[180:183], v[188:191], v[44:47]
	v_mfma_f32_16x16x32_bf16 v[36:39], v[168:171], v[196:199], v[36:39]
	v_mfma_f32_16x16x32_bf16 v[28:31], v[180:183], v[196:199], v[28:31]
	v_mfma_f32_16x16x32_bf16 v[20:23], v[168:171], v[204:207], v[20:23]
	v_mfma_f32_16x16x32_bf16 v[12:15], v[180:183], v[204:207], v[12:15]
	v_mfma_f32_16x16x32_bf16 v[4:7], v[168:171], v[212:215], v[4:7]
	v_mfma_f32_16x16x32_bf16 v[0:3], v[180:183], v[212:215], v[0:3]
	v_mfma_f32_16x16x32_bf16 v[52:55], v[176:179], v[192:195], v[52:55]
	v_mfma_f32_16x16x32_bf16 v[44:47], v[184:187], v[192:195], v[44:47]
	v_mfma_f32_16x16x32_bf16 v[36:39], v[176:179], v[200:203], v[36:39]
	v_mfma_f32_16x16x32_bf16 v[28:31], v[184:187], v[200:203], v[28:31]
	v_mfma_f32_16x16x32_bf16 v[20:23], v[176:179], v[208:211], v[20:23]
	v_mfma_f32_16x16x32_bf16 v[12:15], v[184:187], v[208:211], v[12:15]
	v_mfma_f32_16x16x32_bf16 v[4:7], v[176:179], v[216:219], v[4:7]
	v_mfma_f32_16x16x32_bf16 v[0:3], v[184:187], v[216:219], v[0:3]
	s_setprio 0
	s_barrier
	s_add_i32 s64, s64, 2
	s_add_u32 s42, s42, 0x100
	s_addc_u32 s43, s43, 0
	s_add_u32 s62, s62, 0x100
	s_addc_u32 s63, s63, 0
	s_cmpk_gt_u32 s64, 0xa9
	s_cbranch_scc1 .Lpeel_exit_6

.Lpeel_exit_6:
	s_and_b64 vcc, exec, s[20:21]
	s_cbranch_vccz .LBB0_926
	s_barrier
